# v32 plus: s_setprio flips removed from K loops, end-of-phase bookkeeping moved into MFMA block, K-loop heads aligned to 256 B
# speedup vs baseline: 1.0323x; 1.0047x over previous
.LBB0_270:
	s_ashr_i32 s11, s10, 31
	v_cmp_lt_i64_e32 vcc, s[14:15], v[152:153]
	s_lshl_b64 s[14:15], s[10:11], 19
	s_add_u32 s14, s68, s14
	s_addc_u32 s15, s69, s15
	s_and_b64 s[20:21], vcc, exec
	s_cselect_b32 s11, s15, s5
	s_cselect_b32 s43, s14, s4
	s_ashr_i32 s3, s2, 31
	s_lshl_b64 s[20:21], s[2:3], 19
	s_add_u32 s22, s25, s20
	s_addc_u32 s23, s36, s21
	s_and_b64 s[20:21], vcc, exec
	s_cselect_b32 s3, s23, s9
	s_cselect_b32 s73, s22, s8
	s_add_u32 s4, s4, 0x40080
	s_addc_u32 s5, s5, 0
	s_add_u32 s74, s8, 0x100
	v_mov_b32_e32 v0, 0
	s_addc_u32 s75, s9, 0
	s_mov_b32 s78, -2
	s_waitcnt lgkmcnt(0)
	.p2align	8
	s_add_u32 s8, s4, 0xfffc0080
	s_addc_u32 s9, s5, -1
	s_add_i32 s79, 0, 0x10000
	v_add_u32_e32 v142, s79, v159
	ds_read_b128 v[138:141], v142
	ds_read_b128 v[162:165], v142 offset:1024
	ds_read_b128 v[166:169], v142 offset:2048
	ds_read_b128 v[170:173], v142 offset:3072
	s_cmp_eq_u32 s78, 12
	s_cselect_b32 s21, s11, s9
	s_cselect_b32 s20, s43, s8
	s_cselect_b32 s9, s3, s75
	s_cselect_b32 s8, s73, s74
	v_lshl_add_u64 v[142:143], s[4:5], 0, v[134:135]
	s_add_i32 m0, s44, 0xc000
	ds_read_b128 v[188:191], v161
	ds_read_b128 v[196:199], v161 offset:2048
	ds_read_b128 v[204:207], v161 offset:4096
	ds_read_b128 v[212:215], v161 offset:6144
	ds_read_b128 v[192:195], v161 offset:1024
	ds_read_b128 v[200:203], v161 offset:3072
	ds_read_b128 v[208:211], v161 offset:5120
	ds_read_b128 v[216:219], v161 offset:7168
	global_load_lds_dwordx4 v[142:143], off
	v_lshl_add_u64 v[142:143], s[4:5], 0, v[136:137]
	s_add_i32 m0, s44, 0xe000
	s_nop 0
	global_load_lds_dwordx4 v[142:143], off
	s_waitcnt lgkmcnt(8)
	s_barrier
	s_waitcnt lgkmcnt(7)
	v_mfma_f32_16x16x32_bf16 v[124:127], v[138:141], v[188:191], 0
	v_mfma_f32_16x16x32_bf16 v[120:123], v[166:169], v[188:191], 0
	s_waitcnt lgkmcnt(6)
	v_mfma_f32_16x16x32_bf16 v[108:111], v[138:141], v[196:199], 0
	v_mfma_f32_16x16x32_bf16 v[104:107], v[166:169], v[196:199], 0
	s_waitcnt lgkmcnt(5)
	v_mfma_f32_16x16x32_bf16 v[92:95], v[138:141], v[204:207], 0
	v_mfma_f32_16x16x32_bf16 v[88:91], v[166:169], v[204:207], 0
	s_waitcnt lgkmcnt(4)
	v_mfma_f32_16x16x32_bf16 v[76:79], v[138:141], v[212:215], 0
	v_mfma_f32_16x16x32_bf16 v[72:75], v[166:169], v[212:215], 0
	s_waitcnt lgkmcnt(3)
	v_mfma_f32_16x16x32_bf16 v[124:127], v[162:165], v[192:195], v[124:127]
	v_mfma_f32_16x16x32_bf16 v[120:123], v[170:173], v[192:195], v[120:123]
	s_waitcnt lgkmcnt(2)
	v_mfma_f32_16x16x32_bf16 v[108:111], v[162:165], v[200:203], v[108:111]
	v_mfma_f32_16x16x32_bf16 v[104:107], v[170:173], v[200:203], v[104:107]
	s_waitcnt lgkmcnt(1)
	v_mfma_f32_16x16x32_bf16 v[92:95], v[162:165], v[208:211], v[92:95]
	v_mfma_f32_16x16x32_bf16 v[88:91], v[170:173], v[208:211], v[88:91]
	s_waitcnt lgkmcnt(0)
	v_mfma_f32_16x16x32_bf16 v[76:79], v[162:165], v[216:219], v[76:79]
	v_mfma_f32_16x16x32_bf16 v[72:75], v[170:173], v[216:219], v[72:75]
	s_barrier
	s_add_i32 s84, 0, 0x14000
	v_add_u32_e32 v142, s84, v159
	s_add_i32 s79, s79, s37
	ds_read_b128 v[220:223], v142
	ds_read_b128 v[224:227], v142 offset:1024
	ds_read_b128 v[228:231], v142 offset:2048
	ds_read_b128 v[232:235], v142 offset:3072
	v_lshl_add_u64 v[142:143], s[8:9], 0, v[148:149]
	s_mov_b32 m0, s79
	v_lshl_add_u64 v[174:175], s[8:9], 0, v[128:129]
	global_load_lds_dwordx4 v[142:143], off
	s_add_i32 m0, s79, 0x2000
	s_nop 0
	global_load_lds_dwordx4 v[174:175], off
	s_barrier
	s_waitcnt lgkmcnt(3)
	v_mfma_f32_16x16x32_bf16 v[116:119], v[220:223], v[188:191], 0
	s_waitcnt lgkmcnt(1)
	v_mfma_f32_16x16x32_bf16 v[112:115], v[228:231], v[188:191], 0
	v_mfma_f32_16x16x32_bf16 v[100:103], v[220:223], v[196:199], 0
	v_mfma_f32_16x16x32_bf16 v[96:99], v[228:231], v[196:199], 0
	v_mfma_f32_16x16x32_bf16 v[84:87], v[220:223], v[204:207], 0
	v_mfma_f32_16x16x32_bf16 v[80:83], v[228:231], v[204:207], 0
	v_mfma_f32_16x16x32_bf16 v[68:71], v[220:223], v[212:215], 0
	v_mfma_f32_16x16x32_bf16 v[64:67], v[228:231], v[212:215], 0
	v_mfma_f32_16x16x32_bf16 v[116:119], v[224:227], v[192:195], v[116:119]
	s_waitcnt lgkmcnt(0)
	v_mfma_f32_16x16x32_bf16 v[112:115], v[232:235], v[192:195], v[112:115]
	v_mfma_f32_16x16x32_bf16 v[100:103], v[224:227], v[200:203], v[100:103]
	v_mfma_f32_16x16x32_bf16 v[96:99], v[232:235], v[200:203], v[96:99]
	s_mov_b32 m0, s44
	v_lshl_add_u64 v[236:237], s[20:21], 0, v[132:133]
	v_mfma_f32_16x16x32_bf16 v[84:87], v[224:227], v[208:211], v[84:87]
	v_mfma_f32_16x16x32_bf16 v[80:83], v[232:235], v[208:211], v[80:83]
	v_mfma_f32_16x16x32_bf16 v[68:71], v[224:227], v[216:219], v[68:71]
	v_mfma_f32_16x16x32_bf16 v[64:67], v[232:235], v[216:219], v[64:67]
	s_barrier
	ds_read_b128 v[188:191], v161 offset:16384
	ds_read_b128 v[196:199], v161 offset:18432
	ds_read_b128 v[204:207], v161 offset:20480
	ds_read_b128 v[212:215], v161 offset:22528
	ds_read_b128 v[192:195], v161 offset:17408
	ds_read_b128 v[200:203], v161 offset:19456
	ds_read_b128 v[208:211], v161 offset:21504
	ds_read_b128 v[216:219], v161 offset:23552
	global_load_lds_dwordx4 v[236:237], off
	v_lshl_add_u64 v[238:239], s[20:21], 0, v[130:131]
	s_mov_b32 m0, s45
	s_nop 0
	global_load_lds_dwordx4 v[238:239], off
	s_barrier
	s_waitcnt lgkmcnt(7)
	v_mfma_f32_16x16x32_bf16 v[60:63], v[138:141], v[188:191], 0
	v_mfma_f32_16x16x32_bf16 v[56:59], v[166:169], v[188:191], 0
	s_waitcnt lgkmcnt(6)
	v_mfma_f32_16x16x32_bf16 v[44:47], v[138:141], v[196:199], 0
	v_mfma_f32_16x16x32_bf16 v[40:43], v[166:169], v[196:199], 0
	s_waitcnt lgkmcnt(5)
	v_mfma_f32_16x16x32_bf16 v[28:31], v[138:141], v[204:207], 0
	v_mfma_f32_16x16x32_bf16 v[24:27], v[166:169], v[204:207], 0
	s_waitcnt lgkmcnt(4)
	v_mfma_f32_16x16x32_bf16 v[12:15], v[138:141], v[212:215], 0
	v_mfma_f32_16x16x32_bf16 v[8:11], v[166:169], v[212:215], 0
	s_waitcnt lgkmcnt(3)
	v_mfma_f32_16x16x32_bf16 v[60:63], v[162:165], v[192:195], v[60:63]
	v_mfma_f32_16x16x32_bf16 v[56:59], v[170:173], v[192:195], v[56:59]
	s_waitcnt lgkmcnt(2)
	v_mfma_f32_16x16x32_bf16 v[44:47], v[162:165], v[200:203], v[44:47]
	v_mfma_f32_16x16x32_bf16 v[40:43], v[170:173], v[200:203], v[40:43]
	s_waitcnt lgkmcnt(1)
	v_mfma_f32_16x16x32_bf16 v[28:31], v[162:165], v[208:211], v[28:31]
	v_mfma_f32_16x16x32_bf16 v[24:27], v[170:173], v[208:211], v[24:27]
	s_waitcnt lgkmcnt(0)
	v_mfma_f32_16x16x32_bf16 v[12:15], v[162:165], v[216:219], v[12:15]
	v_mfma_f32_16x16x32_bf16 v[8:11], v[170:173], v[216:219], v[8:11]
	s_barrier
	s_add_u32 s80, s8, 0x40000
	s_addc_u32 s81, s9, 0
	s_add_i32 s79, s84, s37
	v_lshl_add_u64 v[138:139], s[80:81], 0, v[148:149]
	s_mov_b32 m0, s79
	s_nop 0
	global_load_lds_dwordx4 v[138:139], off
	v_lshl_add_u64 v[138:139], s[80:81], 0, v[128:129]
	s_add_i32 m0, s79, 0x2000
	s_nop 0
	global_load_lds_dwordx4 v[138:139], off
	s_waitcnt vmcnt(6)
	s_barrier
	v_mfma_f32_16x16x32_bf16 v[52:55], v[220:223], v[188:191], 0
	v_mfma_f32_16x16x32_bf16 v[48:51], v[228:231], v[188:191], 0
	v_mfma_f32_16x16x32_bf16 v[36:39], v[220:223], v[196:199], 0
	v_mfma_f32_16x16x32_bf16 v[32:35], v[228:231], v[196:199], 0
	v_mfma_f32_16x16x32_bf16 v[20:23], v[220:223], v[204:207], 0
	v_mfma_f32_16x16x32_bf16 v[16:19], v[228:231], v[204:207], 0
	v_mfma_f32_16x16x32_bf16 v[4:7], v[220:223], v[212:215], 0
	v_mfma_f32_16x16x32_bf16 v[0:3], v[228:231], v[212:215], 0
	v_mfma_f32_16x16x32_bf16 v[52:55], v[224:227], v[192:195], v[52:55]
	v_mfma_f32_16x16x32_bf16 v[48:51], v[232:235], v[192:195], v[48:51]
	v_mfma_f32_16x16x32_bf16 v[36:39], v[224:227], v[200:203], v[36:39]
	v_mfma_f32_16x16x32_bf16 v[32:35], v[232:235], v[200:203], v[32:35]
	s_add_i32 s79, 0, 0x18000
	v_add_u32_e32 v170, s79, v159
	v_mfma_f32_16x16x32_bf16 v[20:23], v[224:227], v[208:211], v[20:23]
	v_mfma_f32_16x16x32_bf16 v[16:19], v[232:235], v[208:211], v[16:19]
	v_mfma_f32_16x16x32_bf16 v[4:7], v[224:227], v[216:219], v[4:7]
	v_mfma_f32_16x16x32_bf16 v[0:3], v[232:235], v[216:219], v[0:3]
	s_barrier
	ds_read_b128 v[138:141], v170
	ds_read_b128 v[162:165], v170 offset:1024
	ds_read_b128 v[166:169], v170 offset:2048
	ds_read_b128 v[170:173], v170 offset:3072
	s_add_u32 s20, s20, 0x40000
	s_addc_u32 s21, s21, 0
	s_mov_b32 m0, s46
	v_lshl_add_u64 v[220:221], s[20:21], 0, v[132:133]
	ds_read_b128 v[188:191], v161 offset:32768
	ds_read_b128 v[196:199], v161 offset:34816
	ds_read_b128 v[204:207], v161 offset:36864
	ds_read_b128 v[212:215], v161 offset:38912
	ds_read_b128 v[192:195], v161 offset:33792
	ds_read_b128 v[200:203], v161 offset:35840
	ds_read_b128 v[208:211], v161 offset:37888
	ds_read_b128 v[216:219], v161 offset:39936
	global_load_lds_dwordx4 v[220:221], off
	v_lshl_add_u64 v[220:221], s[20:21], 0, v[130:131]
	s_mov_b32 m0, s47
	s_nop 0
	global_load_lds_dwordx4 v[220:221], off
	s_waitcnt lgkmcnt(8)
	s_barrier
	s_waitcnt lgkmcnt(7)
	v_mfma_f32_16x16x32_bf16 v[124:127], v[138:141], v[188:191], v[124:127]
	v_mfma_f32_16x16x32_bf16 v[120:123], v[166:169], v[188:191], v[120:123]
	s_waitcnt lgkmcnt(6)
	v_mfma_f32_16x16x32_bf16 v[108:111], v[138:141], v[196:199], v[108:111]
	v_mfma_f32_16x16x32_bf16 v[104:107], v[166:169], v[196:199], v[104:107]
	s_waitcnt lgkmcnt(5)
	v_mfma_f32_16x16x32_bf16 v[92:95], v[138:141], v[204:207], v[92:95]
	v_mfma_f32_16x16x32_bf16 v[88:91], v[166:169], v[204:207], v[88:91]
	s_waitcnt lgkmcnt(4)
	v_mfma_f32_16x16x32_bf16 v[76:79], v[138:141], v[212:215], v[76:79]
	v_mfma_f32_16x16x32_bf16 v[72:75], v[166:169], v[212:215], v[72:75]
	s_waitcnt lgkmcnt(3)
	v_mfma_f32_16x16x32_bf16 v[124:127], v[162:165], v[192:195], v[124:127]
	v_mfma_f32_16x16x32_bf16 v[120:123], v[170:173], v[192:195], v[120:123]
	s_waitcnt lgkmcnt(2)
	v_mfma_f32_16x16x32_bf16 v[108:111], v[162:165], v[200:203], v[108:111]
	v_mfma_f32_16x16x32_bf16 v[104:107], v[170:173], v[200:203], v[104:107]
	s_waitcnt lgkmcnt(1)
	v_mfma_f32_16x16x32_bf16 v[92:95], v[162:165], v[208:211], v[92:95]
	v_mfma_f32_16x16x32_bf16 v[88:91], v[170:173], v[208:211], v[88:91]
	s_waitcnt lgkmcnt(0)
	v_mfma_f32_16x16x32_bf16 v[76:79], v[162:165], v[216:219], v[76:79]
	v_mfma_f32_16x16x32_bf16 v[72:75], v[170:173], v[216:219], v[72:75]
	s_barrier
	s_add_i32 s20, 0, 0x1c000
	s_add_i32 s21, s79, s37
	v_add_u32_e32 v232, s20, v159
	v_lshl_add_u64 v[142:143], v[142:143], 0, s[28:29]
	s_mov_b32 m0, s21
	ds_read_b128 v[220:223], v232
	ds_read_b128 v[224:227], v232 offset:1024
	ds_read_b128 v[228:231], v232 offset:2048
	ds_read_b128 v[232:235], v232 offset:3072
	global_load_lds_dwordx4 v[142:143], off
	v_lshl_add_u64 v[142:143], v[174:175], 0, s[28:29]
	s_add_i32 m0, s21, 0x2000
	s_nop 0
	global_load_lds_dwordx4 v[142:143], off
	s_barrier
	s_waitcnt lgkmcnt(3)
	v_mfma_f32_16x16x32_bf16 v[116:119], v[220:223], v[188:191], v[116:119]
	s_waitcnt lgkmcnt(1)
	v_mfma_f32_16x16x32_bf16 v[112:115], v[228:231], v[188:191], v[112:115]
	v_mfma_f32_16x16x32_bf16 v[100:103], v[220:223], v[196:199], v[100:103]
	v_mfma_f32_16x16x32_bf16 v[96:99], v[228:231], v[196:199], v[96:99]
	v_mfma_f32_16x16x32_bf16 v[84:87], v[220:223], v[204:207], v[84:87]
	v_mfma_f32_16x16x32_bf16 v[80:83], v[228:231], v[204:207], v[80:83]
	v_mfma_f32_16x16x32_bf16 v[68:71], v[220:223], v[212:215], v[68:71]
	v_mfma_f32_16x16x32_bf16 v[64:67], v[228:231], v[212:215], v[64:67]
	v_mfma_f32_16x16x32_bf16 v[116:119], v[224:227], v[192:195], v[116:119]
	s_waitcnt lgkmcnt(0)
	v_mfma_f32_16x16x32_bf16 v[112:115], v[232:235], v[192:195], v[112:115]
	v_mfma_f32_16x16x32_bf16 v[100:103], v[224:227], v[200:203], v[100:103]
	v_mfma_f32_16x16x32_bf16 v[96:99], v[232:235], v[200:203], v[96:99]
	s_mov_b32 m0, s51
	v_lshl_add_u64 v[142:143], v[236:237], 0, s[28:29]
	v_mfma_f32_16x16x32_bf16 v[84:87], v[224:227], v[208:211], v[84:87]
	v_mfma_f32_16x16x32_bf16 v[80:83], v[232:235], v[208:211], v[80:83]
	v_mfma_f32_16x16x32_bf16 v[68:71], v[224:227], v[216:219], v[68:71]
	v_mfma_f32_16x16x32_bf16 v[64:67], v[232:235], v[216:219], v[64:67]
	s_barrier
	ds_read_b128 v[188:191], v161 offset:49152
	ds_read_b128 v[196:199], v161 offset:51200
	ds_read_b128 v[204:207], v161 offset:53248
	ds_read_b128 v[212:215], v161 offset:55296
	ds_read_b128 v[192:195], v161 offset:50176
	ds_read_b128 v[200:203], v161 offset:52224
	ds_read_b128 v[208:211], v161 offset:54272
	ds_read_b128 v[216:219], v161 offset:56320
	global_load_lds_dwordx4 v[142:143], off
	v_lshl_add_u64 v[142:143], v[238:239], 0, s[28:29]
	s_mov_b32 m0, s64
	s_nop 0
	global_load_lds_dwordx4 v[142:143], off
	s_barrier
	s_waitcnt lgkmcnt(7)
	v_mfma_f32_16x16x32_bf16 v[60:63], v[138:141], v[188:191], v[60:63]
	v_mfma_f32_16x16x32_bf16 v[56:59], v[166:169], v[188:191], v[56:59]
	s_waitcnt lgkmcnt(6)
	v_mfma_f32_16x16x32_bf16 v[44:47], v[138:141], v[196:199], v[44:47]
	v_mfma_f32_16x16x32_bf16 v[40:43], v[166:169], v[196:199], v[40:43]
	s_waitcnt lgkmcnt(5)
	v_mfma_f32_16x16x32_bf16 v[28:31], v[138:141], v[204:207], v[28:31]
	v_mfma_f32_16x16x32_bf16 v[24:27], v[166:169], v[204:207], v[24:27]
	s_waitcnt lgkmcnt(4)
	v_mfma_f32_16x16x32_bf16 v[12:15], v[138:141], v[212:215], v[12:15]
	v_mfma_f32_16x16x32_bf16 v[8:11], v[166:169], v[212:215], v[8:11]
	s_waitcnt lgkmcnt(3)
	v_mfma_f32_16x16x32_bf16 v[60:63], v[162:165], v[192:195], v[60:63]
	v_mfma_f32_16x16x32_bf16 v[56:59], v[170:173], v[192:195], v[56:59]
	s_waitcnt lgkmcnt(2)
	v_mfma_f32_16x16x32_bf16 v[44:47], v[162:165], v[200:203], v[44:47]
	v_mfma_f32_16x16x32_bf16 v[40:43], v[170:173], v[200:203], v[40:43]
	s_waitcnt lgkmcnt(1)
	v_mfma_f32_16x16x32_bf16 v[28:31], v[162:165], v[208:211], v[28:31]
	v_mfma_f32_16x16x32_bf16 v[24:27], v[170:173], v[208:211], v[24:27]
	s_waitcnt lgkmcnt(0)
	v_mfma_f32_16x16x32_bf16 v[12:15], v[162:165], v[216:219], v[12:15]
	v_mfma_f32_16x16x32_bf16 v[8:11], v[170:173], v[216:219], v[8:11]
	s_barrier
	s_add_u32 s8, s8, 0x40080
	s_addc_u32 s9, s9, 0
	s_add_i32 s20, s20, s37
	v_lshl_add_u64 v[138:139], s[8:9], 0, v[148:149]
	s_mov_b32 m0, s20
	s_nop 0
	global_load_lds_dwordx4 v[138:139], off
	v_lshl_add_u64 v[138:139], s[8:9], 0, v[128:129]
	s_add_i32 m0, s20, 0x2000
	s_nop 0
	global_load_lds_dwordx4 v[138:139], off
	s_waitcnt vmcnt(6)
	s_barrier
	v_mfma_f32_16x16x32_bf16 v[52:55], v[220:223], v[188:191], v[52:55]
	v_mfma_f32_16x16x32_bf16 v[48:51], v[228:231], v[188:191], v[48:51]
	v_mfma_f32_16x16x32_bf16 v[36:39], v[220:223], v[196:199], v[36:39]
	v_mfma_f32_16x16x32_bf16 v[32:35], v[228:231], v[196:199], v[32:35]
	v_mfma_f32_16x16x32_bf16 v[20:23], v[220:223], v[204:207], v[20:23]
	v_mfma_f32_16x16x32_bf16 v[16:19], v[228:231], v[204:207], v[16:19]
	v_mfma_f32_16x16x32_bf16 v[4:7], v[220:223], v[212:215], v[4:7]
	v_mfma_f32_16x16x32_bf16 v[0:3], v[228:231], v[212:215], v[0:3]
	v_mfma_f32_16x16x32_bf16 v[52:55], v[224:227], v[192:195], v[52:55]
	v_mfma_f32_16x16x32_bf16 v[48:51], v[232:235], v[192:195], v[48:51]
	v_mfma_f32_16x16x32_bf16 v[36:39], v[224:227], v[200:203], v[36:39]
	v_mfma_f32_16x16x32_bf16 v[32:35], v[232:235], v[200:203], v[32:35]
	s_add_i32 s78, s78, 2
	s_add_u32 s4, s4, 0x100
	s_addc_u32 s5, s5, 0
	s_add_u32 s74, s74, 0x100
	s_addc_u32 s75, s75, 0
	s_cmp_gt_u32 s78, 13
	v_mfma_f32_16x16x32_bf16 v[20:23], v[224:227], v[208:211], v[20:23]
	v_mfma_f32_16x16x32_bf16 v[16:19], v[232:235], v[208:211], v[16:19]
	v_mfma_f32_16x16x32_bf16 v[4:7], v[224:227], v[216:219], v[4:7]
	v_mfma_f32_16x16x32_bf16 v[0:3], v[232:235], v[216:219], v[0:3]
	s_barrier
	s_cbranch_scc1 .Lpeel_after_g0
	.p2align	8
.LBB0_271:
	s_add_u32 s8, s4, 0xfffc0080
	s_addc_u32 s9, s5, -1
	s_add_i32 s79, 0, 0x10000
	v_add_u32_e32 v142, s79, v159
	ds_read_b128 v[138:141], v142
	ds_read_b128 v[162:165], v142 offset:1024
	ds_read_b128 v[166:169], v142 offset:2048
	ds_read_b128 v[170:173], v142 offset:3072
	s_cmp_eq_u32 s78, 12
	s_cselect_b32 s21, s11, s9
	s_cselect_b32 s20, s43, s8
	s_cselect_b32 s9, s3, s75
	s_cselect_b32 s8, s73, s74
	v_lshl_add_u64 v[142:143], s[4:5], 0, v[134:135]
	s_add_i32 m0, s44, 0xc000
	ds_read_b128 v[188:191], v161
	ds_read_b128 v[196:199], v161 offset:2048
	ds_read_b128 v[204:207], v161 offset:4096
	ds_read_b128 v[212:215], v161 offset:6144
	ds_read_b128 v[192:195], v161 offset:1024
	ds_read_b128 v[200:203], v161 offset:3072
	ds_read_b128 v[208:211], v161 offset:5120
	ds_read_b128 v[216:219], v161 offset:7168
	global_load_lds_dwordx4 v[142:143], off
	v_lshl_add_u64 v[142:143], s[4:5], 0, v[136:137]
	s_add_i32 m0, s44, 0xe000
	s_nop 0
	global_load_lds_dwordx4 v[142:143], off
	s_waitcnt lgkmcnt(8)
	s_barrier
	s_waitcnt lgkmcnt(7)
	v_mfma_f32_16x16x32_bf16 v[124:127], v[138:141], v[188:191], v[124:127]
	v_mfma_f32_16x16x32_bf16 v[120:123], v[166:169], v[188:191], v[120:123]
	s_waitcnt lgkmcnt(6)
	v_mfma_f32_16x16x32_bf16 v[108:111], v[138:141], v[196:199], v[108:111]
	v_mfma_f32_16x16x32_bf16 v[104:107], v[166:169], v[196:199], v[104:107]
	s_waitcnt lgkmcnt(5)
	v_mfma_f32_16x16x32_bf16 v[92:95], v[138:141], v[204:207], v[92:95]
	v_mfma_f32_16x16x32_bf16 v[88:91], v[166:169], v[204:207], v[88:91]
	s_waitcnt lgkmcnt(4)
	v_mfma_f32_16x16x32_bf16 v[76:79], v[138:141], v[212:215], v[76:79]
	v_mfma_f32_16x16x32_bf16 v[72:75], v[166:169], v[212:215], v[72:75]
	s_waitcnt lgkmcnt(3)
	v_mfma_f32_16x16x32_bf16 v[124:127], v[162:165], v[192:195], v[124:127]
	v_mfma_f32_16x16x32_bf16 v[120:123], v[170:173], v[192:195], v[120:123]
	s_waitcnt lgkmcnt(2)
	v_mfma_f32_16x16x32_bf16 v[108:111], v[162:165], v[200:203], v[108:111]
	v_mfma_f32_16x16x32_bf16 v[104:107], v[170:173], v[200:203], v[104:107]
	s_waitcnt lgkmcnt(1)
	v_mfma_f32_16x16x32_bf16 v[92:95], v[162:165], v[208:211], v[92:95]
	v_mfma_f32_16x16x32_bf16 v[88:91], v[170:173], v[208:211], v[88:91]
	s_waitcnt lgkmcnt(0)
	v_mfma_f32_16x16x32_bf16 v[76:79], v[162:165], v[216:219], v[76:79]
	v_mfma_f32_16x16x32_bf16 v[72:75], v[170:173], v[216:219], v[72:75]
	s_barrier
	s_add_i32 s84, 0, 0x14000
	v_add_u32_e32 v142, s84, v159
	s_add_i32 s79, s79, s37
	ds_read_b128 v[220:223], v142
	ds_read_b128 v[224:227], v142 offset:1024
	ds_read_b128 v[228:231], v142 offset:2048
	ds_read_b128 v[232:235], v142 offset:3072
	v_lshl_add_u64 v[142:143], s[8:9], 0, v[148:149]
	s_mov_b32 m0, s79
	v_lshl_add_u64 v[174:175], s[8:9], 0, v[128:129]
	global_load_lds_dwordx4 v[142:143], off
	s_add_i32 m0, s79, 0x2000
	s_nop 0
	global_load_lds_dwordx4 v[174:175], off
	s_barrier
	s_waitcnt lgkmcnt(3)
	v_mfma_f32_16x16x32_bf16 v[116:119], v[220:223], v[188:191], v[116:119]
	s_waitcnt lgkmcnt(1)
	v_mfma_f32_16x16x32_bf16 v[112:115], v[228:231], v[188:191], v[112:115]
	v_mfma_f32_16x16x32_bf16 v[100:103], v[220:223], v[196:199], v[100:103]
	v_mfma_f32_16x16x32_bf16 v[96:99], v[228:231], v[196:199], v[96:99]
	v_mfma_f32_16x16x32_bf16 v[84:87], v[220:223], v[204:207], v[84:87]
	v_mfma_f32_16x16x32_bf16 v[80:83], v[228:231], v[204:207], v[80:83]
	v_mfma_f32_16x16x32_bf16 v[68:71], v[220:223], v[212:215], v[68:71]
	v_mfma_f32_16x16x32_bf16 v[64:67], v[228:231], v[212:215], v[64:67]
	v_mfma_f32_16x16x32_bf16 v[116:119], v[224:227], v[192:195], v[116:119]
	s_waitcnt lgkmcnt(0)
	v_mfma_f32_16x16x32_bf16 v[112:115], v[232:235], v[192:195], v[112:115]
	v_mfma_f32_16x16x32_bf16 v[100:103], v[224:227], v[200:203], v[100:103]
	v_mfma_f32_16x16x32_bf16 v[96:99], v[232:235], v[200:203], v[96:99]
	s_mov_b32 m0, s44
	v_lshl_add_u64 v[236:237], s[20:21], 0, v[132:133]
	v_mfma_f32_16x16x32_bf16 v[84:87], v[224:227], v[208:211], v[84:87]
	v_mfma_f32_16x16x32_bf16 v[80:83], v[232:235], v[208:211], v[80:83]
	v_mfma_f32_16x16x32_bf16 v[68:71], v[224:227], v[216:219], v[68:71]
	v_mfma_f32_16x16x32_bf16 v[64:67], v[232:235], v[216:219], v[64:67]
	s_barrier
	ds_read_b128 v[188:191], v161 offset:16384
	ds_read_b128 v[196:199], v161 offset:18432
	ds_read_b128 v[204:207], v161 offset:20480
	ds_read_b128 v[212:215], v161 offset:22528
	ds_read_b128 v[192:195], v161 offset:17408
	ds_read_b128 v[200:203], v161 offset:19456
	ds_read_b128 v[208:211], v161 offset:21504
	ds_read_b128 v[216:219], v161 offset:23552
	global_load_lds_dwordx4 v[236:237], off
	v_lshl_add_u64 v[238:239], s[20:21], 0, v[130:131]
	s_mov_b32 m0, s45
	s_nop 0
	global_load_lds_dwordx4 v[238:239], off
	s_barrier
	s_waitcnt lgkmcnt(7)
	v_mfma_f32_16x16x32_bf16 v[60:63], v[138:141], v[188:191], v[60:63]
	v_mfma_f32_16x16x32_bf16 v[56:59], v[166:169], v[188:191], v[56:59]
	s_waitcnt lgkmcnt(6)
	v_mfma_f32_16x16x32_bf16 v[44:47], v[138:141], v[196:199], v[44:47]
	v_mfma_f32_16x16x32_bf16 v[40:43], v[166:169], v[196:199], v[40:43]
	s_waitcnt lgkmcnt(5)
	v_mfma_f32_16x16x32_bf16 v[28:31], v[138:141], v[204:207], v[28:31]
	v_mfma_f32_16x16x32_bf16 v[24:27], v[166:169], v[204:207], v[24:27]
	s_waitcnt lgkmcnt(4)
	v_mfma_f32_16x16x32_bf16 v[12:15], v[138:141], v[212:215], v[12:15]
	v_mfma_f32_16x16x32_bf16 v[8:11], v[166:169], v[212:215], v[8:11]
	s_waitcnt lgkmcnt(3)
	v_mfma_f32_16x16x32_bf16 v[60:63], v[162:165], v[192:195], v[60:63]
	v_mfma_f32_16x16x32_bf16 v[56:59], v[170:173], v[192:195], v[56:59]
	s_waitcnt lgkmcnt(2)
	v_mfma_f32_16x16x32_bf16 v[44:47], v[162:165], v[200:203], v[44:47]
	v_mfma_f32_16x16x32_bf16 v[40:43], v[170:173], v[200:203], v[40:43]
	s_waitcnt lgkmcnt(1)
	v_mfma_f32_16x16x32_bf16 v[28:31], v[162:165], v[208:211], v[28:31]
	v_mfma_f32_16x16x32_bf16 v[24:27], v[170:173], v[208:211], v[24:27]
	s_waitcnt lgkmcnt(0)
	v_mfma_f32_16x16x32_bf16 v[12:15], v[162:165], v[216:219], v[12:15]
	v_mfma_f32_16x16x32_bf16 v[8:11], v[170:173], v[216:219], v[8:11]
	s_barrier
	s_add_u32 s80, s8, 0x40000
	s_addc_u32 s81, s9, 0
	s_add_i32 s79, s84, s37
	v_lshl_add_u64 v[138:139], s[80:81], 0, v[148:149]
	s_mov_b32 m0, s79
	s_nop 0
	global_load_lds_dwordx4 v[138:139], off
	v_lshl_add_u64 v[138:139], s[80:81], 0, v[128:129]
	s_add_i32 m0, s79, 0x2000
	s_nop 0
	global_load_lds_dwordx4 v[138:139], off
	s_waitcnt vmcnt(6)
	s_barrier
	v_mfma_f32_16x16x32_bf16 v[52:55], v[220:223], v[188:191], v[52:55]
	v_mfma_f32_16x16x32_bf16 v[48:51], v[228:231], v[188:191], v[48:51]
	v_mfma_f32_16x16x32_bf16 v[36:39], v[220:223], v[196:199], v[36:39]
	v_mfma_f32_16x16x32_bf16 v[32:35], v[228:231], v[196:199], v[32:35]
	v_mfma_f32_16x16x32_bf16 v[20:23], v[220:223], v[204:207], v[20:23]
	v_mfma_f32_16x16x32_bf16 v[16:19], v[228:231], v[204:207], v[16:19]
	v_mfma_f32_16x16x32_bf16 v[4:7], v[220:223], v[212:215], v[4:7]
	v_mfma_f32_16x16x32_bf16 v[0:3], v[228:231], v[212:215], v[0:3]
	v_mfma_f32_16x16x32_bf16 v[52:55], v[224:227], v[192:195], v[52:55]
	v_mfma_f32_16x16x32_bf16 v[48:51], v[232:235], v[192:195], v[48:51]
	v_mfma_f32_16x16x32_bf16 v[36:39], v[224:227], v[200:203], v[36:39]
	v_mfma_f32_16x16x32_bf16 v[32:35], v[232:235], v[200:203], v[32:35]
	s_add_i32 s79, 0, 0x18000
	v_add_u32_e32 v170, s79, v159
	v_mfma_f32_16x16x32_bf16 v[20:23], v[224:227], v[208:211], v[20:23]
	v_mfma_f32_16x16x32_bf16 v[16:19], v[232:235], v[208:211], v[16:19]
	v_mfma_f32_16x16x32_bf16 v[4:7], v[224:227], v[216:219], v[4:7]
	v_mfma_f32_16x16x32_bf16 v[0:3], v[232:235], v[216:219], v[0:3]
	s_barrier
	ds_read_b128 v[138:141], v170
	ds_read_b128 v[162:165], v170 offset:1024
	ds_read_b128 v[166:169], v170 offset:2048
	ds_read_b128 v[170:173], v170 offset:3072
	s_add_u32 s20, s20, 0x40000
	s_addc_u32 s21, s21, 0
	s_mov_b32 m0, s46
	v_lshl_add_u64 v[220:221], s[20:21], 0, v[132:133]
	ds_read_b128 v[188:191], v161 offset:32768
	ds_read_b128 v[196:199], v161 offset:34816
	ds_read_b128 v[204:207], v161 offset:36864
	ds_read_b128 v[212:215], v161 offset:38912
	ds_read_b128 v[192:195], v161 offset:33792
	ds_read_b128 v[200:203], v161 offset:35840
	ds_read_b128 v[208:211], v161 offset:37888
	ds_read_b128 v[216:219], v161 offset:39936
	global_load_lds_dwordx4 v[220:221], off
	v_lshl_add_u64 v[220:221], s[20:21], 0, v[130:131]
	s_mov_b32 m0, s47
	s_nop 0
	global_load_lds_dwordx4 v[220:221], off
	s_waitcnt lgkmcnt(8)
	s_barrier
	s_waitcnt lgkmcnt(7)
	v_mfma_f32_16x16x32_bf16 v[124:127], v[138:141], v[188:191], v[124:127]
	v_mfma_f32_16x16x32_bf16 v[120:123], v[166:169], v[188:191], v[120:123]
	s_waitcnt lgkmcnt(6)
	v_mfma_f32_16x16x32_bf16 v[108:111], v[138:141], v[196:199], v[108:111]
	v_mfma_f32_16x16x32_bf16 v[104:107], v[166:169], v[196:199], v[104:107]
	s_waitcnt lgkmcnt(5)
	v_mfma_f32_16x16x32_bf16 v[92:95], v[138:141], v[204:207], v[92:95]
	v_mfma_f32_16x16x32_bf16 v[88:91], v[166:169], v[204:207], v[88:91]
	s_waitcnt lgkmcnt(4)
	v_mfma_f32_16x16x32_bf16 v[76:79], v[138:141], v[212:215], v[76:79]
	v_mfma_f32_16x16x32_bf16 v[72:75], v[166:169], v[212:215], v[72:75]
	s_waitcnt lgkmcnt(3)
	v_mfma_f32_16x16x32_bf16 v[124:127], v[162:165], v[192:195], v[124:127]
	v_mfma_f32_16x16x32_bf16 v[120:123], v[170:173], v[192:195], v[120:123]
	s_waitcnt lgkmcnt(2)
	v_mfma_f32_16x16x32_bf16 v[108:111], v[162:165], v[200:203], v[108:111]
	v_mfma_f32_16x16x32_bf16 v[104:107], v[170:173], v[200:203], v[104:107]
	s_waitcnt lgkmcnt(1)
	v_mfma_f32_16x16x32_bf16 v[92:95], v[162:165], v[208:211], v[92:95]
	v_mfma_f32_16x16x32_bf16 v[88:91], v[170:173], v[208:211], v[88:91]
	s_waitcnt lgkmcnt(0)
	v_mfma_f32_16x16x32_bf16 v[76:79], v[162:165], v[216:219], v[76:79]
	v_mfma_f32_16x16x32_bf16 v[72:75], v[170:173], v[216:219], v[72:75]
	s_barrier
	s_add_i32 s20, 0, 0x1c000
	s_add_i32 s21, s79, s37
	v_add_u32_e32 v232, s20, v159
	v_lshl_add_u64 v[142:143], v[142:143], 0, s[28:29]
	s_mov_b32 m0, s21
	ds_read_b128 v[220:223], v232
	ds_read_b128 v[224:227], v232 offset:1024
	ds_read_b128 v[228:231], v232 offset:2048
	ds_read_b128 v[232:235], v232 offset:3072
	global_load_lds_dwordx4 v[142:143], off
	v_lshl_add_u64 v[142:143], v[174:175], 0, s[28:29]
	s_add_i32 m0, s21, 0x2000
	s_nop 0
	global_load_lds_dwordx4 v[142:143], off
	s_barrier
	s_waitcnt lgkmcnt(3)
	v_mfma_f32_16x16x32_bf16 v[116:119], v[220:223], v[188:191], v[116:119]
	s_waitcnt lgkmcnt(1)
	v_mfma_f32_16x16x32_bf16 v[112:115], v[228:231], v[188:191], v[112:115]
	v_mfma_f32_16x16x32_bf16 v[100:103], v[220:223], v[196:199], v[100:103]
	v_mfma_f32_16x16x32_bf16 v[96:99], v[228:231], v[196:199], v[96:99]
	v_mfma_f32_16x16x32_bf16 v[84:87], v[220:223], v[204:207], v[84:87]
	v_mfma_f32_16x16x32_bf16 v[80:83], v[228:231], v[204:207], v[80:83]
	v_mfma_f32_16x16x32_bf16 v[68:71], v[220:223], v[212:215], v[68:71]
	v_mfma_f32_16x16x32_bf16 v[64:67], v[228:231], v[212:215], v[64:67]
	v_mfma_f32_16x16x32_bf16 v[116:119], v[224:227], v[192:195], v[116:119]
	s_waitcnt lgkmcnt(0)
	v_mfma_f32_16x16x32_bf16 v[112:115], v[232:235], v[192:195], v[112:115]
	v_mfma_f32_16x16x32_bf16 v[100:103], v[224:227], v[200:203], v[100:103]
	v_mfma_f32_16x16x32_bf16 v[96:99], v[232:235], v[200:203], v[96:99]
	s_mov_b32 m0, s51
	v_lshl_add_u64 v[142:143], v[236:237], 0, s[28:29]
	v_mfma_f32_16x16x32_bf16 v[84:87], v[224:227], v[208:211], v[84:87]
	v_mfma_f32_16x16x32_bf16 v[80:83], v[232:235], v[208:211], v[80:83]
	v_mfma_f32_16x16x32_bf16 v[68:71], v[224:227], v[216:219], v[68:71]
	v_mfma_f32_16x16x32_bf16 v[64:67], v[232:235], v[216:219], v[64:67]
	s_barrier
	ds_read_b128 v[188:191], v161 offset:49152
	ds_read_b128 v[196:199], v161 offset:51200
	ds_read_b128 v[204:207], v161 offset:53248
	ds_read_b128 v[212:215], v161 offset:55296
	ds_read_b128 v[192:195], v161 offset:50176
	ds_read_b128 v[200:203], v161 offset:52224
	ds_read_b128 v[208:211], v161 offset:54272
	ds_read_b128 v[216:219], v161 offset:56320
	global_load_lds_dwordx4 v[142:143], off
	v_lshl_add_u64 v[142:143], v[238:239], 0, s[28:29]
	s_mov_b32 m0, s64
	s_nop 0
	global_load_lds_dwordx4 v[142:143], off
	s_barrier
	s_waitcnt lgkmcnt(7)
	v_mfma_f32_16x16x32_bf16 v[60:63], v[138:141], v[188:191], v[60:63]
	v_mfma_f32_16x16x32_bf16 v[56:59], v[166:169], v[188:191], v[56:59]
	s_waitcnt lgkmcnt(6)
	v_mfma_f32_16x16x32_bf16 v[44:47], v[138:141], v[196:199], v[44:47]
	v_mfma_f32_16x16x32_bf16 v[40:43], v[166:169], v[196:199], v[40:43]
	s_waitcnt lgkmcnt(5)
	v_mfma_f32_16x16x32_bf16 v[28:31], v[138:141], v[204:207], v[28:31]
	v_mfma_f32_16x16x32_bf16 v[24:27], v[166:169], v[204:207], v[24:27]
	s_waitcnt lgkmcnt(4)
	v_mfma_f32_16x16x32_bf16 v[12:15], v[138:141], v[212:215], v[12:15]
	v_mfma_f32_16x16x32_bf16 v[8:11], v[166:169], v[212:215], v[8:11]
	s_waitcnt lgkmcnt(3)
	v_mfma_f32_16x16x32_bf16 v[60:63], v[162:165], v[192:195], v[60:63]
	v_mfma_f32_16x16x32_bf16 v[56:59], v[170:173], v[192:195], v[56:59]
	s_waitcnt lgkmcnt(2)
	v_mfma_f32_16x16x32_bf16 v[44:47], v[162:165], v[200:203], v[44:47]
	v_mfma_f32_16x16x32_bf16 v[40:43], v[170:173], v[200:203], v[40:43]
	s_waitcnt lgkmcnt(1)
	v_mfma_f32_16x16x32_bf16 v[28:31], v[162:165], v[208:211], v[28:31]
	v_mfma_f32_16x16x32_bf16 v[24:27], v[170:173], v[208:211], v[24:27]
	s_waitcnt lgkmcnt(0)
	v_mfma_f32_16x16x32_bf16 v[12:15], v[162:165], v[216:219], v[12:15]
	v_mfma_f32_16x16x32_bf16 v[8:11], v[170:173], v[216:219], v[8:11]
	s_barrier
	s_add_u32 s8, s8, 0x40080
	s_addc_u32 s9, s9, 0
	s_add_i32 s20, s20, s37
	v_lshl_add_u64 v[138:139], s[8:9], 0, v[148:149]
	s_mov_b32 m0, s20
	s_nop 0
	global_load_lds_dwordx4 v[138:139], off
	v_lshl_add_u64 v[138:139], s[8:9], 0, v[128:129]
	s_add_i32 m0, s20, 0x2000
	s_nop 0
	global_load_lds_dwordx4 v[138:139], off
	s_waitcnt vmcnt(6)
	s_barrier
	v_mfma_f32_16x16x32_bf16 v[52:55], v[220:223], v[188:191], v[52:55]
	v_mfma_f32_16x16x32_bf16 v[48:51], v[228:231], v[188:191], v[48:51]
	v_mfma_f32_16x16x32_bf16 v[36:39], v[220:223], v[196:199], v[36:39]
	v_mfma_f32_16x16x32_bf16 v[32:35], v[228:231], v[196:199], v[32:35]
	v_mfma_f32_16x16x32_bf16 v[20:23], v[220:223], v[204:207], v[20:23]
	v_mfma_f32_16x16x32_bf16 v[16:19], v[228:231], v[204:207], v[16:19]
	v_mfma_f32_16x16x32_bf16 v[4:7], v[220:223], v[212:215], v[4:7]
	v_mfma_f32_16x16x32_bf16 v[0:3], v[228:231], v[212:215], v[0:3]
	v_mfma_f32_16x16x32_bf16 v[52:55], v[224:227], v[192:195], v[52:55]
	v_mfma_f32_16x16x32_bf16 v[48:51], v[232:235], v[192:195], v[48:51]
	v_mfma_f32_16x16x32_bf16 v[36:39], v[224:227], v[200:203], v[36:39]
	v_mfma_f32_16x16x32_bf16 v[32:35], v[232:235], v[200:203], v[32:35]
	s_add_i32 s78, s78, 2
	s_add_u32 s4, s4, 0x100
	s_addc_u32 s5, s5, 0
	s_add_u32 s74, s74, 0x100
	s_addc_u32 s75, s75, 0
	s_cmp_gt_u32 s78, 13
	v_mfma_f32_16x16x32_bf16 v[20:23], v[224:227], v[208:211], v[20:23]
	v_mfma_f32_16x16x32_bf16 v[16:19], v[232:235], v[208:211], v[16:19]
	v_mfma_f32_16x16x32_bf16 v[4:7], v[224:227], v[216:219], v[4:7]
	v_mfma_f32_16x16x32_bf16 v[0:3], v[232:235], v[216:219], v[0:3]
	s_barrier
	s_cbranch_scc0 .LBB0_271

.LBB0_489:
	s_add_u32 s0, s44, 0x80
	s_addc_u32 s1, s45, 0
	s_add_u32 vcc_lo, s42, 0x100
	v_mov_b32_e32 v0, 0
	s_addc_u32 vcc_hi, s43, 0
	s_mov_b32 s42, 0
	.p2align	8
	s_add_i32 s94, s42, 2
	s_add_u32 s44, s0, 0x80
	s_addc_u32 s43, s1, 0
	s_add_i32 s95, 0, 0x10000
	v_add_u32_e32 v140, s95, v173
	ds_read_b128 v[128:131], v140
	ds_read_b128 v[132:135], v140 offset:1024
	ds_read_b128 v[136:139], v140 offset:2048
	ds_read_b128 v[140:143], v140 offset:3072
	s_cmp_eq_u32 s79, s42
	s_cselect_b32 s42, s20, s44
	s_cselect_b32 s43, s21, s43
	s_cselect_b32 s45, s41, vcc_hi
	s_cselect_b32 s44, s40, vcc_lo
	v_lshl_add_u64 v[216:217], s[0:1], 0, v[164:165]
	s_add_i32 m0, s51, 0xc000
	ds_read_b128 v[168:171], v175
	ds_read_b128 v[192:195], v175 offset:2048
	ds_read_b128 v[200:203], v175 offset:4096
	ds_read_b128 v[208:211], v175 offset:6144
	ds_read_b128 v[188:191], v175 offset:1024
	ds_read_b128 v[196:199], v175 offset:3072
	ds_read_b128 v[204:207], v175 offset:5120
	ds_read_b128 v[212:215], v175 offset:7168
	global_load_lds_dwordx4 v[216:217], off
	v_lshl_add_u64 v[216:217], s[0:1], 0, v[166:167]
	s_add_i32 m0, s51, 0xe000
	s_nop 0
	global_load_lds_dwordx4 v[216:217], off
	s_waitcnt lgkmcnt(8)
	s_barrier
	s_waitcnt lgkmcnt(7)
	v_mfma_f32_16x16x32_bf16 v[124:127], v[128:131], v[168:171], 0
	v_mfma_f32_16x16x32_bf16 v[120:123], v[136:139], v[168:171], 0
	s_waitcnt lgkmcnt(6)
	v_mfma_f32_16x16x32_bf16 v[112:115], v[128:131], v[192:195], 0
	v_mfma_f32_16x16x32_bf16 v[104:107], v[136:139], v[192:195], 0
	s_waitcnt lgkmcnt(5)
	v_mfma_f32_16x16x32_bf16 v[96:99], v[128:131], v[200:203], 0
	v_mfma_f32_16x16x32_bf16 v[88:91], v[136:139], v[200:203], 0
	s_waitcnt lgkmcnt(4)
	v_mfma_f32_16x16x32_bf16 v[80:83], v[128:131], v[208:211], 0
	v_mfma_f32_16x16x32_bf16 v[72:75], v[136:139], v[208:211], 0
	s_waitcnt lgkmcnt(3)
	v_mfma_f32_16x16x32_bf16 v[124:127], v[132:135], v[188:191], v[124:127]
	v_mfma_f32_16x16x32_bf16 v[120:123], v[140:143], v[188:191], v[120:123]
	s_waitcnt lgkmcnt(2)
	v_mfma_f32_16x16x32_bf16 v[112:115], v[132:135], v[196:199], v[112:115]
	v_mfma_f32_16x16x32_bf16 v[104:107], v[140:143], v[196:199], v[104:107]
	s_waitcnt lgkmcnt(1)
	v_mfma_f32_16x16x32_bf16 v[96:99], v[132:135], v[204:207], v[96:99]
	v_mfma_f32_16x16x32_bf16 v[88:91], v[140:143], v[204:207], v[88:91]
	s_waitcnt lgkmcnt(0)
	v_mfma_f32_16x16x32_bf16 v[80:83], v[132:135], v[212:215], v[80:83]
	v_mfma_f32_16x16x32_bf16 v[72:75], v[140:143], v[212:215], v[72:75]
	s_barrier
	s_add_i32 s96, 0, 0x14000
	s_add_i32 s95, s95, s50
	v_add_u32_e32 v228, s96, v173
	v_lshl_add_u64 v[232:233], s[44:45], 0, v[148:149]
	s_mov_b32 m0, s95
	ds_read_b128 v[216:219], v228
	ds_read_b128 v[220:223], v228 offset:1024
	ds_read_b128 v[224:227], v228 offset:2048
	ds_read_b128 v[228:231], v228 offset:3072
	global_load_lds_dwordx4 v[232:233], off
	v_lshl_add_u64 v[234:235], s[44:45], 0, v[158:159]
	s_add_i32 m0, s95, 0x2000
	s_nop 0
	global_load_lds_dwordx4 v[234:235], off
	s_barrier
	s_waitcnt lgkmcnt(3)
	v_mfma_f32_16x16x32_bf16 v[116:119], v[216:219], v[168:171], 0
	s_waitcnt lgkmcnt(1)
	v_mfma_f32_16x16x32_bf16 v[108:111], v[224:227], v[168:171], 0
	v_mfma_f32_16x16x32_bf16 v[100:103], v[216:219], v[192:195], 0
	v_mfma_f32_16x16x32_bf16 v[92:95], v[224:227], v[192:195], 0
	v_mfma_f32_16x16x32_bf16 v[84:87], v[216:219], v[200:203], 0
	v_mfma_f32_16x16x32_bf16 v[76:79], v[224:227], v[200:203], 0
	v_mfma_f32_16x16x32_bf16 v[68:71], v[216:219], v[208:211], 0
	v_mfma_f32_16x16x32_bf16 v[64:67], v[224:227], v[208:211], 0
	v_mfma_f32_16x16x32_bf16 v[116:119], v[220:223], v[188:191], v[116:119]
	s_waitcnt lgkmcnt(0)
	v_mfma_f32_16x16x32_bf16 v[108:111], v[228:231], v[188:191], v[108:111]
	v_mfma_f32_16x16x32_bf16 v[100:103], v[220:223], v[196:199], v[100:103]
	v_mfma_f32_16x16x32_bf16 v[92:95], v[228:231], v[196:199], v[92:95]
	s_mov_b32 m0, s51
	v_lshl_add_u64 v[236:237], s[42:43], 0, v[162:163]
	v_mfma_f32_16x16x32_bf16 v[84:87], v[220:223], v[204:207], v[84:87]
	v_mfma_f32_16x16x32_bf16 v[76:79], v[228:231], v[204:207], v[76:79]
	v_mfma_f32_16x16x32_bf16 v[68:71], v[220:223], v[212:215], v[68:71]
	v_mfma_f32_16x16x32_bf16 v[64:67], v[228:231], v[212:215], v[64:67]
	s_barrier
	ds_read_b128 v[168:171], v175 offset:16384
	ds_read_b128 v[192:195], v175 offset:18432
	ds_read_b128 v[200:203], v175 offset:20480
	ds_read_b128 v[208:211], v175 offset:22528
	ds_read_b128 v[188:191], v175 offset:17408
	ds_read_b128 v[196:199], v175 offset:19456
	ds_read_b128 v[204:207], v175 offset:21504
	ds_read_b128 v[212:215], v175 offset:23552
	global_load_lds_dwordx4 v[236:237], off
	v_lshl_add_u64 v[238:239], s[42:43], 0, v[160:161]
	s_mov_b32 m0, s74
	s_nop 0
	global_load_lds_dwordx4 v[238:239], off
	s_barrier
	s_waitcnt lgkmcnt(7)
	v_mfma_f32_16x16x32_bf16 v[60:63], v[128:131], v[168:171], 0
	v_mfma_f32_16x16x32_bf16 v[56:59], v[136:139], v[168:171], 0
	s_waitcnt lgkmcnt(6)
	v_mfma_f32_16x16x32_bf16 v[52:55], v[128:131], v[192:195], 0
	v_mfma_f32_16x16x32_bf16 v[44:47], v[136:139], v[192:195], 0
	s_waitcnt lgkmcnt(5)
	v_mfma_f32_16x16x32_bf16 v[36:39], v[128:131], v[200:203], 0
	v_mfma_f32_16x16x32_bf16 v[28:31], v[136:139], v[200:203], 0
	s_waitcnt lgkmcnt(4)
	v_mfma_f32_16x16x32_bf16 v[20:23], v[128:131], v[208:211], 0
	v_mfma_f32_16x16x32_bf16 v[12:15], v[136:139], v[208:211], 0
	s_waitcnt lgkmcnt(3)
	v_mfma_f32_16x16x32_bf16 v[60:63], v[132:135], v[188:191], v[60:63]
	v_mfma_f32_16x16x32_bf16 v[56:59], v[140:143], v[188:191], v[56:59]
	s_waitcnt lgkmcnt(2)
	v_mfma_f32_16x16x32_bf16 v[52:55], v[132:135], v[196:199], v[52:55]
	v_mfma_f32_16x16x32_bf16 v[44:47], v[140:143], v[196:199], v[44:47]
	s_waitcnt lgkmcnt(1)
	v_mfma_f32_16x16x32_bf16 v[36:39], v[132:135], v[204:207], v[36:39]
	v_mfma_f32_16x16x32_bf16 v[28:31], v[140:143], v[204:207], v[28:31]
	s_waitcnt lgkmcnt(0)
	v_mfma_f32_16x16x32_bf16 v[20:23], v[132:135], v[212:215], v[20:23]
	v_mfma_f32_16x16x32_bf16 v[12:15], v[140:143], v[212:215], v[12:15]
	s_barrier
	s_add_u32 s44, s44, s11
	s_addc_u32 s45, s45, 0
	s_add_i32 s95, s96, s50
	v_lshl_add_u64 v[240:241], s[44:45], 0, v[148:149]
	s_mov_b32 m0, s95
	v_lshl_add_u64 v[242:243], s[44:45], 0, v[158:159]
	global_load_lds_dwordx4 v[240:241], off
	s_add_i32 m0, s95, 0x2000
	s_nop 0
	global_load_lds_dwordx4 v[242:243], off
	s_waitcnt vmcnt(6)
	s_barrier
	v_mfma_f32_16x16x32_bf16 v[48:51], v[216:219], v[168:171], 0
	v_mfma_f32_16x16x32_bf16 v[40:43], v[224:227], v[168:171], 0
	v_mfma_f32_16x16x32_bf16 v[32:35], v[216:219], v[192:195], 0
	v_mfma_f32_16x16x32_bf16 v[24:27], v[224:227], v[192:195], 0
	v_mfma_f32_16x16x32_bf16 v[16:19], v[216:219], v[200:203], 0
	v_mfma_f32_16x16x32_bf16 v[8:11], v[224:227], v[200:203], 0
	v_mfma_f32_16x16x32_bf16 v[4:7], v[216:219], v[208:211], 0
	v_mfma_f32_16x16x32_bf16 v[0:3], v[224:227], v[208:211], 0
	v_mfma_f32_16x16x32_bf16 v[48:51], v[220:223], v[188:191], v[48:51]
	v_mfma_f32_16x16x32_bf16 v[40:43], v[228:231], v[188:191], v[40:43]
	v_mfma_f32_16x16x32_bf16 v[32:35], v[220:223], v[196:199], v[32:35]
	v_mfma_f32_16x16x32_bf16 v[24:27], v[228:231], v[196:199], v[24:27]
	s_add_i32 s44, 0, 0x18000
	v_add_u32_e32 v140, s44, v173
	v_mfma_f32_16x16x32_bf16 v[16:19], v[220:223], v[204:207], v[16:19]
	v_mfma_f32_16x16x32_bf16 v[8:11], v[228:231], v[204:207], v[8:11]
	v_mfma_f32_16x16x32_bf16 v[4:7], v[220:223], v[212:215], v[4:7]
	v_mfma_f32_16x16x32_bf16 v[0:3], v[228:231], v[212:215], v[0:3]
	s_barrier
	ds_read_b128 v[128:131], v140
	ds_read_b128 v[132:135], v140 offset:1024
	ds_read_b128 v[136:139], v140 offset:2048
	ds_read_b128 v[140:143], v140 offset:3072
	s_add_u32 s42, s42, s84
	s_addc_u32 s43, s43, 0
	s_mov_b32 m0, s75
	v_lshl_add_u64 v[216:217], s[42:43], 0, v[162:163]
	ds_read_b128 v[168:171], v175 offset:32768
	ds_read_b128 v[192:195], v175 offset:34816
	ds_read_b128 v[200:203], v175 offset:36864
	ds_read_b128 v[208:211], v175 offset:38912
	ds_read_b128 v[188:191], v175 offset:33792
	ds_read_b128 v[196:199], v175 offset:35840
	ds_read_b128 v[204:207], v175 offset:37888
	ds_read_b128 v[212:215], v175 offset:39936
	global_load_lds_dwordx4 v[216:217], off
	v_lshl_add_u64 v[216:217], s[42:43], 0, v[160:161]
	s_mov_b32 m0, s78
	s_nop 0
	global_load_lds_dwordx4 v[216:217], off
	s_waitcnt lgkmcnt(8)
	s_barrier
	s_waitcnt lgkmcnt(7)
	v_mfma_f32_16x16x32_bf16 v[124:127], v[128:131], v[168:171], v[124:127]
	v_mfma_f32_16x16x32_bf16 v[120:123], v[136:139], v[168:171], v[120:123]
	s_waitcnt lgkmcnt(6)
	v_mfma_f32_16x16x32_bf16 v[112:115], v[128:131], v[192:195], v[112:115]
	v_mfma_f32_16x16x32_bf16 v[104:107], v[136:139], v[192:195], v[104:107]
	s_waitcnt lgkmcnt(5)
	v_mfma_f32_16x16x32_bf16 v[96:99], v[128:131], v[200:203], v[96:99]
	v_mfma_f32_16x16x32_bf16 v[88:91], v[136:139], v[200:203], v[88:91]
	s_waitcnt lgkmcnt(4)
	v_mfma_f32_16x16x32_bf16 v[80:83], v[128:131], v[208:211], v[80:83]
	v_mfma_f32_16x16x32_bf16 v[72:75], v[136:139], v[208:211], v[72:75]
	s_waitcnt lgkmcnt(3)
	v_mfma_f32_16x16x32_bf16 v[124:127], v[132:135], v[188:191], v[124:127]
	v_mfma_f32_16x16x32_bf16 v[120:123], v[140:143], v[188:191], v[120:123]
	s_waitcnt lgkmcnt(2)
	v_mfma_f32_16x16x32_bf16 v[112:115], v[132:135], v[196:199], v[112:115]
	v_mfma_f32_16x16x32_bf16 v[104:107], v[140:143], v[196:199], v[104:107]
	s_waitcnt lgkmcnt(1)
	v_mfma_f32_16x16x32_bf16 v[96:99], v[132:135], v[204:207], v[96:99]
	v_mfma_f32_16x16x32_bf16 v[88:91], v[140:143], v[204:207], v[88:91]
	s_waitcnt lgkmcnt(0)
	v_mfma_f32_16x16x32_bf16 v[80:83], v[132:135], v[212:215], v[80:83]
	v_mfma_f32_16x16x32_bf16 v[72:75], v[140:143], v[212:215], v[72:75]
	s_barrier
	s_add_i32 s42, 0, 0x1c000
	s_add_i32 s43, s44, s50
	v_add_u32_e32 v228, s42, v173
	v_lshl_add_u64 v[232:233], v[232:233], 0, s[28:29]
	s_mov_b32 m0, s43
	ds_read_b128 v[216:219], v228
	ds_read_b128 v[220:223], v228 offset:1024
	ds_read_b128 v[224:227], v228 offset:2048
	ds_read_b128 v[228:231], v228 offset:3072
	global_load_lds_dwordx4 v[232:233], off
	v_lshl_add_u64 v[232:233], v[234:235], 0, s[28:29]
	s_add_i32 m0, s43, 0x2000
	s_nop 0
	global_load_lds_dwordx4 v[232:233], off
	s_barrier
	s_waitcnt lgkmcnt(3)
	v_mfma_f32_16x16x32_bf16 v[116:119], v[216:219], v[168:171], v[116:119]
	s_waitcnt lgkmcnt(1)
	v_mfma_f32_16x16x32_bf16 v[108:111], v[224:227], v[168:171], v[108:111]
	v_mfma_f32_16x16x32_bf16 v[100:103], v[216:219], v[192:195], v[100:103]
	v_mfma_f32_16x16x32_bf16 v[92:95], v[224:227], v[192:195], v[92:95]
	v_mfma_f32_16x16x32_bf16 v[84:87], v[216:219], v[200:203], v[84:87]
	v_mfma_f32_16x16x32_bf16 v[76:79], v[224:227], v[200:203], v[76:79]
	v_mfma_f32_16x16x32_bf16 v[68:71], v[216:219], v[208:211], v[68:71]
	v_mfma_f32_16x16x32_bf16 v[64:67], v[224:227], v[208:211], v[64:67]
	v_mfma_f32_16x16x32_bf16 v[116:119], v[220:223], v[188:191], v[116:119]
	s_waitcnt lgkmcnt(0)
	v_mfma_f32_16x16x32_bf16 v[108:111], v[228:231], v[188:191], v[108:111]
	v_mfma_f32_16x16x32_bf16 v[100:103], v[220:223], v[196:199], v[100:103]
	v_mfma_f32_16x16x32_bf16 v[92:95], v[228:231], v[196:199], v[92:95]
	s_mov_b32 m0, s80
	v_lshl_add_u64 v[232:233], v[236:237], 0, s[28:29]
	v_mfma_f32_16x16x32_bf16 v[84:87], v[220:223], v[204:207], v[84:87]
	v_mfma_f32_16x16x32_bf16 v[76:79], v[228:231], v[204:207], v[76:79]
	v_mfma_f32_16x16x32_bf16 v[68:71], v[220:223], v[212:215], v[68:71]
	v_mfma_f32_16x16x32_bf16 v[64:67], v[228:231], v[212:215], v[64:67]
	s_barrier
	ds_read_b128 v[168:171], v175 offset:49152
	ds_read_b128 v[192:195], v175 offset:51200
	ds_read_b128 v[200:203], v175 offset:53248
	ds_read_b128 v[208:211], v175 offset:55296
	ds_read_b128 v[188:191], v175 offset:50176
	ds_read_b128 v[196:199], v175 offset:52224
	ds_read_b128 v[204:207], v175 offset:54272
	ds_read_b128 v[212:215], v175 offset:56320
	global_load_lds_dwordx4 v[232:233], off
	v_lshl_add_u64 v[232:233], v[238:239], 0, s[28:29]
	s_mov_b32 m0, s81
	s_nop 0
	global_load_lds_dwordx4 v[232:233], off
	s_barrier
	s_waitcnt lgkmcnt(7)
	v_mfma_f32_16x16x32_bf16 v[60:63], v[128:131], v[168:171], v[60:63]
	v_mfma_f32_16x16x32_bf16 v[56:59], v[136:139], v[168:171], v[56:59]
	s_waitcnt lgkmcnt(6)
	v_mfma_f32_16x16x32_bf16 v[52:55], v[128:131], v[192:195], v[52:55]
	v_mfma_f32_16x16x32_bf16 v[44:47], v[136:139], v[192:195], v[44:47]
	s_waitcnt lgkmcnt(5)
	v_mfma_f32_16x16x32_bf16 v[36:39], v[128:131], v[200:203], v[36:39]
	v_mfma_f32_16x16x32_bf16 v[28:31], v[136:139], v[200:203], v[28:31]
	s_waitcnt lgkmcnt(4)
	v_mfma_f32_16x16x32_bf16 v[20:23], v[128:131], v[208:211], v[20:23]
	v_mfma_f32_16x16x32_bf16 v[12:15], v[136:139], v[208:211], v[12:15]
	s_waitcnt lgkmcnt(3)
	v_mfma_f32_16x16x32_bf16 v[60:63], v[132:135], v[188:191], v[60:63]
	v_mfma_f32_16x16x32_bf16 v[56:59], v[140:143], v[188:191], v[56:59]
	s_waitcnt lgkmcnt(2)
	v_mfma_f32_16x16x32_bf16 v[52:55], v[132:135], v[196:199], v[52:55]
	v_mfma_f32_16x16x32_bf16 v[44:47], v[140:143], v[196:199], v[44:47]
	s_waitcnt lgkmcnt(1)
	v_mfma_f32_16x16x32_bf16 v[36:39], v[132:135], v[204:207], v[36:39]
	v_mfma_f32_16x16x32_bf16 v[28:31], v[140:143], v[204:207], v[28:31]
	s_waitcnt lgkmcnt(0)
	v_mfma_f32_16x16x32_bf16 v[20:23], v[132:135], v[212:215], v[20:23]
	v_mfma_f32_16x16x32_bf16 v[12:15], v[140:143], v[212:215], v[12:15]
	s_barrier
	s_add_i32 s42, s42, s50
	v_lshl_add_u64 v[128:129], v[240:241], 0, s[28:29]
	s_mov_b32 m0, s42
	s_nop 0
	global_load_lds_dwordx4 v[128:129], off
	v_lshl_add_u64 v[128:129], v[242:243], 0, s[28:29]
	s_add_i32 m0, s42, 0x2000
	s_nop 0
	global_load_lds_dwordx4 v[128:129], off
	s_waitcnt vmcnt(6)
	s_barrier
	v_mfma_f32_16x16x32_bf16 v[48:51], v[216:219], v[168:171], v[48:51]
	v_mfma_f32_16x16x32_bf16 v[40:43], v[224:227], v[168:171], v[40:43]
	v_mfma_f32_16x16x32_bf16 v[32:35], v[216:219], v[192:195], v[32:35]
	v_mfma_f32_16x16x32_bf16 v[24:27], v[224:227], v[192:195], v[24:27]
	v_mfma_f32_16x16x32_bf16 v[16:19], v[216:219], v[200:203], v[16:19]
	v_mfma_f32_16x16x32_bf16 v[8:11], v[224:227], v[200:203], v[8:11]
	v_mfma_f32_16x16x32_bf16 v[4:7], v[216:219], v[208:211], v[4:7]
	v_mfma_f32_16x16x32_bf16 v[0:3], v[224:227], v[208:211], v[0:3]
	v_mfma_f32_16x16x32_bf16 v[48:51], v[220:223], v[188:191], v[48:51]
	v_mfma_f32_16x16x32_bf16 v[40:43], v[228:231], v[188:191], v[40:43]
	v_mfma_f32_16x16x32_bf16 v[32:35], v[220:223], v[196:199], v[32:35]
	v_mfma_f32_16x16x32_bf16 v[24:27], v[228:231], v[196:199], v[24:27]
	s_add_u32 s0, s0, 0x100
	s_addc_u32 s1, s1, 0
	s_add_u32 vcc_lo, vcc_lo, 0x100
	s_addc_u32 vcc_hi, vcc_hi, 0
	s_cmp_ge_u32 s94, s88
	s_mov_b32 s42, s94
	v_mfma_f32_16x16x32_bf16 v[16:19], v[220:223], v[204:207], v[16:19]
	v_mfma_f32_16x16x32_bf16 v[8:11], v[228:231], v[204:207], v[8:11]
	v_mfma_f32_16x16x32_bf16 v[4:7], v[220:223], v[212:215], v[4:7]
	v_mfma_f32_16x16x32_bf16 v[0:3], v[228:231], v[212:215], v[0:3]
	s_barrier
	s_cbranch_scc1 .Lpeel_after_g2
	.p2align	8
.LBB0_490:
	s_add_i32 s94, s42, 2
	s_add_u32 s44, s0, 0x80
	s_addc_u32 s43, s1, 0
	s_add_i32 s95, 0, 0x10000
	v_add_u32_e32 v140, s95, v173
	ds_read_b128 v[128:131], v140
	ds_read_b128 v[132:135], v140 offset:1024
	ds_read_b128 v[136:139], v140 offset:2048
	ds_read_b128 v[140:143], v140 offset:3072
	s_cmp_eq_u32 s79, s42
	s_cselect_b32 s42, s20, s44
	s_cselect_b32 s43, s21, s43
	s_cselect_b32 s45, s41, vcc_hi
	s_cselect_b32 s44, s40, vcc_lo
	v_lshl_add_u64 v[216:217], s[0:1], 0, v[164:165]
	s_add_i32 m0, s51, 0xc000
	ds_read_b128 v[168:171], v175
	ds_read_b128 v[192:195], v175 offset:2048
	ds_read_b128 v[200:203], v175 offset:4096
	ds_read_b128 v[208:211], v175 offset:6144
	ds_read_b128 v[188:191], v175 offset:1024
	ds_read_b128 v[196:199], v175 offset:3072
	ds_read_b128 v[204:207], v175 offset:5120
	ds_read_b128 v[212:215], v175 offset:7168
	global_load_lds_dwordx4 v[216:217], off
	v_lshl_add_u64 v[216:217], s[0:1], 0, v[166:167]
	s_add_i32 m0, s51, 0xe000
	s_nop 0
	global_load_lds_dwordx4 v[216:217], off
	s_waitcnt lgkmcnt(8)
	s_barrier
	s_waitcnt lgkmcnt(7)
	v_mfma_f32_16x16x32_bf16 v[124:127], v[128:131], v[168:171], v[124:127]
	v_mfma_f32_16x16x32_bf16 v[120:123], v[136:139], v[168:171], v[120:123]
	s_waitcnt lgkmcnt(6)
	v_mfma_f32_16x16x32_bf16 v[112:115], v[128:131], v[192:195], v[112:115]
	v_mfma_f32_16x16x32_bf16 v[104:107], v[136:139], v[192:195], v[104:107]
	s_waitcnt lgkmcnt(5)
	v_mfma_f32_16x16x32_bf16 v[96:99], v[128:131], v[200:203], v[96:99]
	v_mfma_f32_16x16x32_bf16 v[88:91], v[136:139], v[200:203], v[88:91]
	s_waitcnt lgkmcnt(4)
	v_mfma_f32_16x16x32_bf16 v[80:83], v[128:131], v[208:211], v[80:83]
	v_mfma_f32_16x16x32_bf16 v[72:75], v[136:139], v[208:211], v[72:75]
	s_waitcnt lgkmcnt(3)
	v_mfma_f32_16x16x32_bf16 v[124:127], v[132:135], v[188:191], v[124:127]
	v_mfma_f32_16x16x32_bf16 v[120:123], v[140:143], v[188:191], v[120:123]
	s_waitcnt lgkmcnt(2)
	v_mfma_f32_16x16x32_bf16 v[112:115], v[132:135], v[196:199], v[112:115]
	v_mfma_f32_16x16x32_bf16 v[104:107], v[140:143], v[196:199], v[104:107]
	s_waitcnt lgkmcnt(1)
	v_mfma_f32_16x16x32_bf16 v[96:99], v[132:135], v[204:207], v[96:99]
	v_mfma_f32_16x16x32_bf16 v[88:91], v[140:143], v[204:207], v[88:91]
	s_waitcnt lgkmcnt(0)
	v_mfma_f32_16x16x32_bf16 v[80:83], v[132:135], v[212:215], v[80:83]
	v_mfma_f32_16x16x32_bf16 v[72:75], v[140:143], v[212:215], v[72:75]
	s_barrier
	s_add_i32 s96, 0, 0x14000
	s_add_i32 s95, s95, s50
	v_add_u32_e32 v228, s96, v173
	v_lshl_add_u64 v[232:233], s[44:45], 0, v[148:149]
	s_mov_b32 m0, s95
	ds_read_b128 v[216:219], v228
	ds_read_b128 v[220:223], v228 offset:1024
	ds_read_b128 v[224:227], v228 offset:2048
	ds_read_b128 v[228:231], v228 offset:3072
	global_load_lds_dwordx4 v[232:233], off
	v_lshl_add_u64 v[234:235], s[44:45], 0, v[158:159]
	s_add_i32 m0, s95, 0x2000
	s_nop 0
	global_load_lds_dwordx4 v[234:235], off
	s_barrier
	s_waitcnt lgkmcnt(3)
	v_mfma_f32_16x16x32_bf16 v[116:119], v[216:219], v[168:171], v[116:119]
	s_waitcnt lgkmcnt(1)
	v_mfma_f32_16x16x32_bf16 v[108:111], v[224:227], v[168:171], v[108:111]
	v_mfma_f32_16x16x32_bf16 v[100:103], v[216:219], v[192:195], v[100:103]
	v_mfma_f32_16x16x32_bf16 v[92:95], v[224:227], v[192:195], v[92:95]
	v_mfma_f32_16x16x32_bf16 v[84:87], v[216:219], v[200:203], v[84:87]
	v_mfma_f32_16x16x32_bf16 v[76:79], v[224:227], v[200:203], v[76:79]
	v_mfma_f32_16x16x32_bf16 v[68:71], v[216:219], v[208:211], v[68:71]
	v_mfma_f32_16x16x32_bf16 v[64:67], v[224:227], v[208:211], v[64:67]
	v_mfma_f32_16x16x32_bf16 v[116:119], v[220:223], v[188:191], v[116:119]
	s_waitcnt lgkmcnt(0)
	v_mfma_f32_16x16x32_bf16 v[108:111], v[228:231], v[188:191], v[108:111]
	v_mfma_f32_16x16x32_bf16 v[100:103], v[220:223], v[196:199], v[100:103]
	v_mfma_f32_16x16x32_bf16 v[92:95], v[228:231], v[196:199], v[92:95]
	s_mov_b32 m0, s51
	v_lshl_add_u64 v[236:237], s[42:43], 0, v[162:163]
	v_mfma_f32_16x16x32_bf16 v[84:87], v[220:223], v[204:207], v[84:87]
	v_mfma_f32_16x16x32_bf16 v[76:79], v[228:231], v[204:207], v[76:79]
	v_mfma_f32_16x16x32_bf16 v[68:71], v[220:223], v[212:215], v[68:71]
	v_mfma_f32_16x16x32_bf16 v[64:67], v[228:231], v[212:215], v[64:67]
	s_barrier
	ds_read_b128 v[168:171], v175 offset:16384
	ds_read_b128 v[192:195], v175 offset:18432
	ds_read_b128 v[200:203], v175 offset:20480
	ds_read_b128 v[208:211], v175 offset:22528
	ds_read_b128 v[188:191], v175 offset:17408
	ds_read_b128 v[196:199], v175 offset:19456
	ds_read_b128 v[204:207], v175 offset:21504
	ds_read_b128 v[212:215], v175 offset:23552
	global_load_lds_dwordx4 v[236:237], off
	v_lshl_add_u64 v[238:239], s[42:43], 0, v[160:161]
	s_mov_b32 m0, s74
	s_nop 0
	global_load_lds_dwordx4 v[238:239], off
	s_barrier
	s_waitcnt lgkmcnt(7)
	v_mfma_f32_16x16x32_bf16 v[60:63], v[128:131], v[168:171], v[60:63]
	v_mfma_f32_16x16x32_bf16 v[56:59], v[136:139], v[168:171], v[56:59]
	s_waitcnt lgkmcnt(6)
	v_mfma_f32_16x16x32_bf16 v[52:55], v[128:131], v[192:195], v[52:55]
	v_mfma_f32_16x16x32_bf16 v[44:47], v[136:139], v[192:195], v[44:47]
	s_waitcnt lgkmcnt(5)
	v_mfma_f32_16x16x32_bf16 v[36:39], v[128:131], v[200:203], v[36:39]
	v_mfma_f32_16x16x32_bf16 v[28:31], v[136:139], v[200:203], v[28:31]
	s_waitcnt lgkmcnt(4)
	v_mfma_f32_16x16x32_bf16 v[20:23], v[128:131], v[208:211], v[20:23]
	v_mfma_f32_16x16x32_bf16 v[12:15], v[136:139], v[208:211], v[12:15]
	s_waitcnt lgkmcnt(3)
	v_mfma_f32_16x16x32_bf16 v[60:63], v[132:135], v[188:191], v[60:63]
	v_mfma_f32_16x16x32_bf16 v[56:59], v[140:143], v[188:191], v[56:59]
	s_waitcnt lgkmcnt(2)
	v_mfma_f32_16x16x32_bf16 v[52:55], v[132:135], v[196:199], v[52:55]
	v_mfma_f32_16x16x32_bf16 v[44:47], v[140:143], v[196:199], v[44:47]
	s_waitcnt lgkmcnt(1)
	v_mfma_f32_16x16x32_bf16 v[36:39], v[132:135], v[204:207], v[36:39]
	v_mfma_f32_16x16x32_bf16 v[28:31], v[140:143], v[204:207], v[28:31]
	s_waitcnt lgkmcnt(0)
	v_mfma_f32_16x16x32_bf16 v[20:23], v[132:135], v[212:215], v[20:23]
	v_mfma_f32_16x16x32_bf16 v[12:15], v[140:143], v[212:215], v[12:15]
	s_barrier
	s_add_u32 s44, s44, s11
	s_addc_u32 s45, s45, 0
	s_add_i32 s95, s96, s50
	v_lshl_add_u64 v[240:241], s[44:45], 0, v[148:149]
	s_mov_b32 m0, s95
	v_lshl_add_u64 v[242:243], s[44:45], 0, v[158:159]
	global_load_lds_dwordx4 v[240:241], off
	s_add_i32 m0, s95, 0x2000
	s_nop 0
	global_load_lds_dwordx4 v[242:243], off
	s_waitcnt vmcnt(6)
	s_barrier
	v_mfma_f32_16x16x32_bf16 v[48:51], v[216:219], v[168:171], v[48:51]
	v_mfma_f32_16x16x32_bf16 v[40:43], v[224:227], v[168:171], v[40:43]
	v_mfma_f32_16x16x32_bf16 v[32:35], v[216:219], v[192:195], v[32:35]
	v_mfma_f32_16x16x32_bf16 v[24:27], v[224:227], v[192:195], v[24:27]
	v_mfma_f32_16x16x32_bf16 v[16:19], v[216:219], v[200:203], v[16:19]
	v_mfma_f32_16x16x32_bf16 v[8:11], v[224:227], v[200:203], v[8:11]
	v_mfma_f32_16x16x32_bf16 v[4:7], v[216:219], v[208:211], v[4:7]
	v_mfma_f32_16x16x32_bf16 v[0:3], v[224:227], v[208:211], v[0:3]
	v_mfma_f32_16x16x32_bf16 v[48:51], v[220:223], v[188:191], v[48:51]
	v_mfma_f32_16x16x32_bf16 v[40:43], v[228:231], v[188:191], v[40:43]
	v_mfma_f32_16x16x32_bf16 v[32:35], v[220:223], v[196:199], v[32:35]
	v_mfma_f32_16x16x32_bf16 v[24:27], v[228:231], v[196:199], v[24:27]
	s_add_i32 s44, 0, 0x18000
	v_add_u32_e32 v140, s44, v173
	v_mfma_f32_16x16x32_bf16 v[16:19], v[220:223], v[204:207], v[16:19]
	v_mfma_f32_16x16x32_bf16 v[8:11], v[228:231], v[204:207], v[8:11]
	v_mfma_f32_16x16x32_bf16 v[4:7], v[220:223], v[212:215], v[4:7]
	v_mfma_f32_16x16x32_bf16 v[0:3], v[228:231], v[212:215], v[0:3]
	s_barrier
	ds_read_b128 v[128:131], v140
	ds_read_b128 v[132:135], v140 offset:1024
	ds_read_b128 v[136:139], v140 offset:2048
	ds_read_b128 v[140:143], v140 offset:3072
	s_add_u32 s42, s42, s84
	s_addc_u32 s43, s43, 0
	s_mov_b32 m0, s75
	v_lshl_add_u64 v[216:217], s[42:43], 0, v[162:163]
	ds_read_b128 v[168:171], v175 offset:32768
	ds_read_b128 v[192:195], v175 offset:34816
	ds_read_b128 v[200:203], v175 offset:36864
	ds_read_b128 v[208:211], v175 offset:38912
	ds_read_b128 v[188:191], v175 offset:33792
	ds_read_b128 v[196:199], v175 offset:35840
	ds_read_b128 v[204:207], v175 offset:37888
	ds_read_b128 v[212:215], v175 offset:39936
	global_load_lds_dwordx4 v[216:217], off
	v_lshl_add_u64 v[216:217], s[42:43], 0, v[160:161]
	s_mov_b32 m0, s78
	s_nop 0
	global_load_lds_dwordx4 v[216:217], off
	s_waitcnt lgkmcnt(8)
	s_barrier
	s_waitcnt lgkmcnt(7)
	v_mfma_f32_16x16x32_bf16 v[124:127], v[128:131], v[168:171], v[124:127]
	v_mfma_f32_16x16x32_bf16 v[120:123], v[136:139], v[168:171], v[120:123]
	s_waitcnt lgkmcnt(6)
	v_mfma_f32_16x16x32_bf16 v[112:115], v[128:131], v[192:195], v[112:115]
	v_mfma_f32_16x16x32_bf16 v[104:107], v[136:139], v[192:195], v[104:107]
	s_waitcnt lgkmcnt(5)
	v_mfma_f32_16x16x32_bf16 v[96:99], v[128:131], v[200:203], v[96:99]
	v_mfma_f32_16x16x32_bf16 v[88:91], v[136:139], v[200:203], v[88:91]
	s_waitcnt lgkmcnt(4)
	v_mfma_f32_16x16x32_bf16 v[80:83], v[128:131], v[208:211], v[80:83]
	v_mfma_f32_16x16x32_bf16 v[72:75], v[136:139], v[208:211], v[72:75]
	s_waitcnt lgkmcnt(3)
	v_mfma_f32_16x16x32_bf16 v[124:127], v[132:135], v[188:191], v[124:127]
	v_mfma_f32_16x16x32_bf16 v[120:123], v[140:143], v[188:191], v[120:123]
	s_waitcnt lgkmcnt(2)
	v_mfma_f32_16x16x32_bf16 v[112:115], v[132:135], v[196:199], v[112:115]
	v_mfma_f32_16x16x32_bf16 v[104:107], v[140:143], v[196:199], v[104:107]
	s_waitcnt lgkmcnt(1)
	v_mfma_f32_16x16x32_bf16 v[96:99], v[132:135], v[204:207], v[96:99]
	v_mfma_f32_16x16x32_bf16 v[88:91], v[140:143], v[204:207], v[88:91]
	s_waitcnt lgkmcnt(0)
	v_mfma_f32_16x16x32_bf16 v[80:83], v[132:135], v[212:215], v[80:83]
	v_mfma_f32_16x16x32_bf16 v[72:75], v[140:143], v[212:215], v[72:75]
	s_barrier
	s_add_i32 s42, 0, 0x1c000
	s_add_i32 s43, s44, s50
	v_add_u32_e32 v228, s42, v173
	v_lshl_add_u64 v[232:233], v[232:233], 0, s[28:29]
	s_mov_b32 m0, s43
	ds_read_b128 v[216:219], v228
	ds_read_b128 v[220:223], v228 offset:1024
	ds_read_b128 v[224:227], v228 offset:2048
	ds_read_b128 v[228:231], v228 offset:3072
	global_load_lds_dwordx4 v[232:233], off
	v_lshl_add_u64 v[232:233], v[234:235], 0, s[28:29]
	s_add_i32 m0, s43, 0x2000
	s_nop 0
	global_load_lds_dwordx4 v[232:233], off
	s_barrier
	s_waitcnt lgkmcnt(3)
	v_mfma_f32_16x16x32_bf16 v[116:119], v[216:219], v[168:171], v[116:119]
	s_waitcnt lgkmcnt(1)
	v_mfma_f32_16x16x32_bf16 v[108:111], v[224:227], v[168:171], v[108:111]
	v_mfma_f32_16x16x32_bf16 v[100:103], v[216:219], v[192:195], v[100:103]
	v_mfma_f32_16x16x32_bf16 v[92:95], v[224:227], v[192:195], v[92:95]
	v_mfma_f32_16x16x32_bf16 v[84:87], v[216:219], v[200:203], v[84:87]
	v_mfma_f32_16x16x32_bf16 v[76:79], v[224:227], v[200:203], v[76:79]
	v_mfma_f32_16x16x32_bf16 v[68:71], v[216:219], v[208:211], v[68:71]
	v_mfma_f32_16x16x32_bf16 v[64:67], v[224:227], v[208:211], v[64:67]
	v_mfma_f32_16x16x32_bf16 v[116:119], v[220:223], v[188:191], v[116:119]
	s_waitcnt lgkmcnt(0)
	v_mfma_f32_16x16x32_bf16 v[108:111], v[228:231], v[188:191], v[108:111]
	v_mfma_f32_16x16x32_bf16 v[100:103], v[220:223], v[196:199], v[100:103]
	v_mfma_f32_16x16x32_bf16 v[92:95], v[228:231], v[196:199], v[92:95]
	s_mov_b32 m0, s80
	v_lshl_add_u64 v[232:233], v[236:237], 0, s[28:29]
	v_mfma_f32_16x16x32_bf16 v[84:87], v[220:223], v[204:207], v[84:87]
	v_mfma_f32_16x16x32_bf16 v[76:79], v[228:231], v[204:207], v[76:79]
	v_mfma_f32_16x16x32_bf16 v[68:71], v[220:223], v[212:215], v[68:71]
	v_mfma_f32_16x16x32_bf16 v[64:67], v[228:231], v[212:215], v[64:67]
	s_barrier
	ds_read_b128 v[168:171], v175 offset:49152
	ds_read_b128 v[192:195], v175 offset:51200
	ds_read_b128 v[200:203], v175 offset:53248
	ds_read_b128 v[208:211], v175 offset:55296
	ds_read_b128 v[188:191], v175 offset:50176
	ds_read_b128 v[196:199], v175 offset:52224
	ds_read_b128 v[204:207], v175 offset:54272
	ds_read_b128 v[212:215], v175 offset:56320
	global_load_lds_dwordx4 v[232:233], off
	v_lshl_add_u64 v[232:233], v[238:239], 0, s[28:29]
	s_mov_b32 m0, s81
	s_nop 0
	global_load_lds_dwordx4 v[232:233], off
	s_barrier
	s_waitcnt lgkmcnt(7)
	v_mfma_f32_16x16x32_bf16 v[60:63], v[128:131], v[168:171], v[60:63]
	v_mfma_f32_16x16x32_bf16 v[56:59], v[136:139], v[168:171], v[56:59]
	s_waitcnt lgkmcnt(6)
	v_mfma_f32_16x16x32_bf16 v[52:55], v[128:131], v[192:195], v[52:55]
	v_mfma_f32_16x16x32_bf16 v[44:47], v[136:139], v[192:195], v[44:47]
	s_waitcnt lgkmcnt(5)
	v_mfma_f32_16x16x32_bf16 v[36:39], v[128:131], v[200:203], v[36:39]
	v_mfma_f32_16x16x32_bf16 v[28:31], v[136:139], v[200:203], v[28:31]
	s_waitcnt lgkmcnt(4)
	v_mfma_f32_16x16x32_bf16 v[20:23], v[128:131], v[208:211], v[20:23]
	v_mfma_f32_16x16x32_bf16 v[12:15], v[136:139], v[208:211], v[12:15]
	s_waitcnt lgkmcnt(3)
	v_mfma_f32_16x16x32_bf16 v[60:63], v[132:135], v[188:191], v[60:63]
	v_mfma_f32_16x16x32_bf16 v[56:59], v[140:143], v[188:191], v[56:59]
	s_waitcnt lgkmcnt(2)
	v_mfma_f32_16x16x32_bf16 v[52:55], v[132:135], v[196:199], v[52:55]
	v_mfma_f32_16x16x32_bf16 v[44:47], v[140:143], v[196:199], v[44:47]
	s_waitcnt lgkmcnt(1)
	v_mfma_f32_16x16x32_bf16 v[36:39], v[132:135], v[204:207], v[36:39]
	v_mfma_f32_16x16x32_bf16 v[28:31], v[140:143], v[204:207], v[28:31]
	s_waitcnt lgkmcnt(0)
	v_mfma_f32_16x16x32_bf16 v[20:23], v[132:135], v[212:215], v[20:23]
	v_mfma_f32_16x16x32_bf16 v[12:15], v[140:143], v[212:215], v[12:15]
	s_barrier
	s_add_i32 s42, s42, s50
	v_lshl_add_u64 v[128:129], v[240:241], 0, s[28:29]
	s_mov_b32 m0, s42
	s_nop 0
	global_load_lds_dwordx4 v[128:129], off
	v_lshl_add_u64 v[128:129], v[242:243], 0, s[28:29]
	s_add_i32 m0, s42, 0x2000
	s_nop 0
	global_load_lds_dwordx4 v[128:129], off
	s_waitcnt vmcnt(6)
	s_barrier
	v_mfma_f32_16x16x32_bf16 v[48:51], v[216:219], v[168:171], v[48:51]
	v_mfma_f32_16x16x32_bf16 v[40:43], v[224:227], v[168:171], v[40:43]
	v_mfma_f32_16x16x32_bf16 v[32:35], v[216:219], v[192:195], v[32:35]
	v_mfma_f32_16x16x32_bf16 v[24:27], v[224:227], v[192:195], v[24:27]
	v_mfma_f32_16x16x32_bf16 v[16:19], v[216:219], v[200:203], v[16:19]
	v_mfma_f32_16x16x32_bf16 v[8:11], v[224:227], v[200:203], v[8:11]
	v_mfma_f32_16x16x32_bf16 v[4:7], v[216:219], v[208:211], v[4:7]
	v_mfma_f32_16x16x32_bf16 v[0:3], v[224:227], v[208:211], v[0:3]
	v_mfma_f32_16x16x32_bf16 v[48:51], v[220:223], v[188:191], v[48:51]
	v_mfma_f32_16x16x32_bf16 v[40:43], v[228:231], v[188:191], v[40:43]
	v_mfma_f32_16x16x32_bf16 v[32:35], v[220:223], v[196:199], v[32:35]
	v_mfma_f32_16x16x32_bf16 v[24:27], v[228:231], v[196:199], v[24:27]
	s_add_u32 s0, s0, 0x100
	s_addc_u32 s1, s1, 0
	s_add_u32 vcc_lo, vcc_lo, 0x100
	s_addc_u32 vcc_hi, vcc_hi, 0
	s_cmp_ge_u32 s94, s88
	s_mov_b32 s42, s94
	v_mfma_f32_16x16x32_bf16 v[16:19], v[220:223], v[204:207], v[16:19]
	v_mfma_f32_16x16x32_bf16 v[8:11], v[228:231], v[204:207], v[8:11]
	v_mfma_f32_16x16x32_bf16 v[4:7], v[220:223], v[212:215], v[4:7]
	v_mfma_f32_16x16x32_bf16 v[0:3], v[228:231], v[212:215], v[0:3]
	s_barrier
	s_cbranch_scc0 .LBB0_490

.LBB0_704:
	s_ashr_i32 s3, s2, 31
	v_cmp_lt_i64_e32 vcc, s[4:5], v[152:153]
	s_lshl_b64 s[4:5], s[2:3], 19
	s_add_u32 s4, s68, s4
	s_addc_u32 s5, s69, s5
	s_and_b64 s[8:9], vcc, exec
	s_cselect_b32 s3, s5, s11
	s_cselect_b32 s45, s4, s10
	s_ashr_i32 s1, s0, 31
	s_lshl_b64 s[8:9], s[0:1], 19
	s_add_u32 s8, s65, s8
	s_addc_u32 s9, s72, s9
	s_and_b64 s[20:21], vcc, exec
	s_cselect_b32 s1, s9, s15
	s_cselect_b32 s46, s8, s14
	s_add_u32 s10, s10, 0x40080
	s_addc_u32 s11, s11, 0
	s_add_u32 s47, s14, 0x100
	v_mov_b32_e32 v0, 0
	s_addc_u32 s50, s15, 0
	s_mov_b32 s51, -2
	.p2align	8
	s_add_u32 s14, s10, 0xfffc0080
	s_addc_u32 s15, s11, -1
	s_add_i32 s73, 0, 0x10000
	v_add_u32_e32 v138, s73, v141
	ds_read_b128 v[158:161], v138
	ds_read_b128 v[162:165], v138 offset:1024
	ds_read_b128 v[166:169], v138 offset:2048
	ds_read_b128 v[170:173], v138 offset:3072
	s_cmp_eq_u32 s51, 12
	s_cselect_b32 s21, s3, s15
	s_cselect_b32 s20, s45, s14
	s_cselect_b32 s15, s1, s50
	s_cselect_b32 s14, s46, s47
	v_lshl_add_u64 v[138:139], s[10:11], 0, v[134:135]
	s_add_i32 m0, s24, 0xc000
	ds_read_b128 v[188:191], v143
	ds_read_b128 v[196:199], v143 offset:2048
	ds_read_b128 v[204:207], v143 offset:4096
	ds_read_b128 v[212:215], v143 offset:6144
	ds_read_b128 v[192:195], v143 offset:1024
	ds_read_b128 v[200:203], v143 offset:3072
	ds_read_b128 v[208:211], v143 offset:5120
	ds_read_b128 v[216:219], v143 offset:7168
	global_load_lds_dwordx4 v[138:139], off
	v_lshl_add_u64 v[138:139], s[10:11], 0, v[136:137]
	s_add_i32 m0, s24, 0xe000
	s_nop 0
	global_load_lds_dwordx4 v[138:139], off
	s_waitcnt lgkmcnt(8)
	s_barrier
	s_waitcnt lgkmcnt(7)
	v_mfma_f32_16x16x32_bf16 v[124:127], v[158:161], v[188:191], 0
	v_mfma_f32_16x16x32_bf16 v[120:123], v[166:169], v[188:191], 0
	s_waitcnt lgkmcnt(6)
	v_mfma_f32_16x16x32_bf16 v[108:111], v[158:161], v[196:199], 0
	v_mfma_f32_16x16x32_bf16 v[104:107], v[166:169], v[196:199], 0
	s_waitcnt lgkmcnt(5)
	v_mfma_f32_16x16x32_bf16 v[92:95], v[158:161], v[204:207], 0
	v_mfma_f32_16x16x32_bf16 v[88:91], v[166:169], v[204:207], 0
	s_waitcnt lgkmcnt(4)
	v_mfma_f32_16x16x32_bf16 v[76:79], v[158:161], v[212:215], 0
	v_mfma_f32_16x16x32_bf16 v[72:75], v[166:169], v[212:215], 0
	s_waitcnt lgkmcnt(3)
	v_mfma_f32_16x16x32_bf16 v[124:127], v[162:165], v[192:195], v[124:127]
	v_mfma_f32_16x16x32_bf16 v[120:123], v[170:173], v[192:195], v[120:123]
	s_waitcnt lgkmcnt(2)
	v_mfma_f32_16x16x32_bf16 v[108:111], v[162:165], v[200:203], v[108:111]
	v_mfma_f32_16x16x32_bf16 v[104:107], v[170:173], v[200:203], v[104:107]
	s_waitcnt lgkmcnt(1)
	v_mfma_f32_16x16x32_bf16 v[92:95], v[162:165], v[208:211], v[92:95]
	v_mfma_f32_16x16x32_bf16 v[88:91], v[170:173], v[208:211], v[88:91]
	s_waitcnt lgkmcnt(0)
	v_mfma_f32_16x16x32_bf16 v[76:79], v[162:165], v[216:219], v[76:79]
	v_mfma_f32_16x16x32_bf16 v[72:75], v[170:173], v[216:219], v[72:75]
	s_barrier
	s_add_i32 s78, 0, 0x14000
	v_add_u32_e32 v138, s78, v141
	s_add_i32 s73, s73, s23
	ds_read_b128 v[220:223], v138
	ds_read_b128 v[224:227], v138 offset:1024
	ds_read_b128 v[228:231], v138 offset:2048
	ds_read_b128 v[232:235], v138 offset:3072
	v_lshl_add_u64 v[138:139], s[14:15], 0, v[148:149]
	s_mov_b32 m0, s73
	v_lshl_add_u64 v[174:175], s[14:15], 0, v[128:129]
	global_load_lds_dwordx4 v[138:139], off
	s_add_i32 m0, s73, 0x2000
	s_nop 0
	global_load_lds_dwordx4 v[174:175], off
	s_barrier
	s_waitcnt lgkmcnt(3)
	v_mfma_f32_16x16x32_bf16 v[116:119], v[220:223], v[188:191], 0
	s_waitcnt lgkmcnt(1)
	v_mfma_f32_16x16x32_bf16 v[112:115], v[228:231], v[188:191], 0
	v_mfma_f32_16x16x32_bf16 v[100:103], v[220:223], v[196:199], 0
	v_mfma_f32_16x16x32_bf16 v[96:99], v[228:231], v[196:199], 0
	v_mfma_f32_16x16x32_bf16 v[84:87], v[220:223], v[204:207], 0
	v_mfma_f32_16x16x32_bf16 v[80:83], v[228:231], v[204:207], 0
	v_mfma_f32_16x16x32_bf16 v[68:71], v[220:223], v[212:215], 0
	v_mfma_f32_16x16x32_bf16 v[64:67], v[228:231], v[212:215], 0
	v_mfma_f32_16x16x32_bf16 v[116:119], v[224:227], v[192:195], v[116:119]
	s_waitcnt lgkmcnt(0)
	v_mfma_f32_16x16x32_bf16 v[112:115], v[232:235], v[192:195], v[112:115]
	v_mfma_f32_16x16x32_bf16 v[100:103], v[224:227], v[200:203], v[100:103]
	v_mfma_f32_16x16x32_bf16 v[96:99], v[232:235], v[200:203], v[96:99]
	s_mov_b32 m0, s24
	v_lshl_add_u64 v[236:237], s[20:21], 0, v[132:133]
	v_mfma_f32_16x16x32_bf16 v[84:87], v[224:227], v[208:211], v[84:87]
	v_mfma_f32_16x16x32_bf16 v[80:83], v[232:235], v[208:211], v[80:83]
	v_mfma_f32_16x16x32_bf16 v[68:71], v[224:227], v[216:219], v[68:71]
	v_mfma_f32_16x16x32_bf16 v[64:67], v[232:235], v[216:219], v[64:67]
	s_barrier
	ds_read_b128 v[188:191], v143 offset:16384
	ds_read_b128 v[196:199], v143 offset:18432
	ds_read_b128 v[204:207], v143 offset:20480
	ds_read_b128 v[212:215], v143 offset:22528
	ds_read_b128 v[192:195], v143 offset:17408
	ds_read_b128 v[200:203], v143 offset:19456
	ds_read_b128 v[208:211], v143 offset:21504
	ds_read_b128 v[216:219], v143 offset:23552
	global_load_lds_dwordx4 v[236:237], off
	v_lshl_add_u64 v[238:239], s[20:21], 0, v[130:131]
	s_mov_b32 m0, s25
	s_nop 0
	global_load_lds_dwordx4 v[238:239], off
	s_barrier
	s_waitcnt lgkmcnt(7)
	v_mfma_f32_16x16x32_bf16 v[60:63], v[158:161], v[188:191], 0
	v_mfma_f32_16x16x32_bf16 v[56:59], v[166:169], v[188:191], 0
	s_waitcnt lgkmcnt(6)
	v_mfma_f32_16x16x32_bf16 v[44:47], v[158:161], v[196:199], 0
	v_mfma_f32_16x16x32_bf16 v[40:43], v[166:169], v[196:199], 0
	s_waitcnt lgkmcnt(5)
	v_mfma_f32_16x16x32_bf16 v[28:31], v[158:161], v[204:207], 0
	v_mfma_f32_16x16x32_bf16 v[24:27], v[166:169], v[204:207], 0
	s_waitcnt lgkmcnt(4)
	v_mfma_f32_16x16x32_bf16 v[12:15], v[158:161], v[212:215], 0
	v_mfma_f32_16x16x32_bf16 v[8:11], v[166:169], v[212:215], 0
	s_waitcnt lgkmcnt(3)
	v_mfma_f32_16x16x32_bf16 v[60:63], v[162:165], v[192:195], v[60:63]
	v_mfma_f32_16x16x32_bf16 v[56:59], v[170:173], v[192:195], v[56:59]
	s_waitcnt lgkmcnt(2)
	v_mfma_f32_16x16x32_bf16 v[44:47], v[162:165], v[200:203], v[44:47]
	v_mfma_f32_16x16x32_bf16 v[40:43], v[170:173], v[200:203], v[40:43]
	s_waitcnt lgkmcnt(1)
	v_mfma_f32_16x16x32_bf16 v[28:31], v[162:165], v[208:211], v[28:31]
	v_mfma_f32_16x16x32_bf16 v[24:27], v[170:173], v[208:211], v[24:27]
	s_waitcnt lgkmcnt(0)
	v_mfma_f32_16x16x32_bf16 v[12:15], v[162:165], v[216:219], v[12:15]
	v_mfma_f32_16x16x32_bf16 v[8:11], v[170:173], v[216:219], v[8:11]
	s_barrier
	s_add_u32 s74, s14, 0x40000
	s_addc_u32 s75, s15, 0
	s_add_i32 s73, s78, s23
	v_lshl_add_u64 v[158:159], s[74:75], 0, v[148:149]
	s_mov_b32 m0, s73
	s_nop 0
	global_load_lds_dwordx4 v[158:159], off
	v_lshl_add_u64 v[158:159], s[74:75], 0, v[128:129]
	s_add_i32 m0, s73, 0x2000
	s_nop 0
	global_load_lds_dwordx4 v[158:159], off
	s_waitcnt vmcnt(6)
	s_barrier
	v_mfma_f32_16x16x32_bf16 v[52:55], v[220:223], v[188:191], 0
	v_mfma_f32_16x16x32_bf16 v[48:51], v[228:231], v[188:191], 0
	v_mfma_f32_16x16x32_bf16 v[36:39], v[220:223], v[196:199], 0
	v_mfma_f32_16x16x32_bf16 v[32:35], v[228:231], v[196:199], 0
	v_mfma_f32_16x16x32_bf16 v[20:23], v[220:223], v[204:207], 0
	v_mfma_f32_16x16x32_bf16 v[16:19], v[228:231], v[204:207], 0
	v_mfma_f32_16x16x32_bf16 v[4:7], v[220:223], v[212:215], 0
	v_mfma_f32_16x16x32_bf16 v[0:3], v[228:231], v[212:215], 0
	v_mfma_f32_16x16x32_bf16 v[52:55], v[224:227], v[192:195], v[52:55]
	v_mfma_f32_16x16x32_bf16 v[48:51], v[232:235], v[192:195], v[48:51]
	v_mfma_f32_16x16x32_bf16 v[36:39], v[224:227], v[200:203], v[36:39]
	v_mfma_f32_16x16x32_bf16 v[32:35], v[232:235], v[200:203], v[32:35]
	s_add_i32 s73, 0, 0x18000
	v_add_u32_e32 v170, s73, v141
	v_mfma_f32_16x16x32_bf16 v[20:23], v[224:227], v[208:211], v[20:23]
	v_mfma_f32_16x16x32_bf16 v[16:19], v[232:235], v[208:211], v[16:19]
	v_mfma_f32_16x16x32_bf16 v[4:7], v[224:227], v[216:219], v[4:7]
	v_mfma_f32_16x16x32_bf16 v[0:3], v[232:235], v[216:219], v[0:3]
	s_barrier
	ds_read_b128 v[158:161], v170
	ds_read_b128 v[162:165], v170 offset:1024
	ds_read_b128 v[166:169], v170 offset:2048
	ds_read_b128 v[170:173], v170 offset:3072
	s_add_u32 s20, s20, 0x40000
	s_addc_u32 s21, s21, 0
	s_mov_b32 m0, s36
	v_lshl_add_u64 v[220:221], s[20:21], 0, v[132:133]
	ds_read_b128 v[188:191], v143 offset:32768
	ds_read_b128 v[196:199], v143 offset:34816
	ds_read_b128 v[204:207], v143 offset:36864
	ds_read_b128 v[212:215], v143 offset:38912
	ds_read_b128 v[192:195], v143 offset:33792
	ds_read_b128 v[200:203], v143 offset:35840
	ds_read_b128 v[208:211], v143 offset:37888
	ds_read_b128 v[216:219], v143 offset:39936
	global_load_lds_dwordx4 v[220:221], off
	v_lshl_add_u64 v[220:221], s[20:21], 0, v[130:131]
	s_mov_b32 m0, s37
	s_nop 0
	global_load_lds_dwordx4 v[220:221], off
	s_waitcnt lgkmcnt(8)
	s_barrier
	s_waitcnt lgkmcnt(7)
	v_mfma_f32_16x16x32_bf16 v[124:127], v[158:161], v[188:191], v[124:127]
	v_mfma_f32_16x16x32_bf16 v[120:123], v[166:169], v[188:191], v[120:123]
	s_waitcnt lgkmcnt(6)
	v_mfma_f32_16x16x32_bf16 v[108:111], v[158:161], v[196:199], v[108:111]
	v_mfma_f32_16x16x32_bf16 v[104:107], v[166:169], v[196:199], v[104:107]
	s_waitcnt lgkmcnt(5)
	v_mfma_f32_16x16x32_bf16 v[92:95], v[158:161], v[204:207], v[92:95]
	v_mfma_f32_16x16x32_bf16 v[88:91], v[166:169], v[204:207], v[88:91]
	s_waitcnt lgkmcnt(4)
	v_mfma_f32_16x16x32_bf16 v[76:79], v[158:161], v[212:215], v[76:79]
	v_mfma_f32_16x16x32_bf16 v[72:75], v[166:169], v[212:215], v[72:75]
	s_waitcnt lgkmcnt(3)
	v_mfma_f32_16x16x32_bf16 v[124:127], v[162:165], v[192:195], v[124:127]
	v_mfma_f32_16x16x32_bf16 v[120:123], v[170:173], v[192:195], v[120:123]
	s_waitcnt lgkmcnt(2)
	v_mfma_f32_16x16x32_bf16 v[108:111], v[162:165], v[200:203], v[108:111]
	v_mfma_f32_16x16x32_bf16 v[104:107], v[170:173], v[200:203], v[104:107]
	s_waitcnt lgkmcnt(1)
	v_mfma_f32_16x16x32_bf16 v[92:95], v[162:165], v[208:211], v[92:95]
	v_mfma_f32_16x16x32_bf16 v[88:91], v[170:173], v[208:211], v[88:91]
	s_waitcnt lgkmcnt(0)
	v_mfma_f32_16x16x32_bf16 v[76:79], v[162:165], v[216:219], v[76:79]
	v_mfma_f32_16x16x32_bf16 v[72:75], v[170:173], v[216:219], v[72:75]
	s_barrier
	s_add_i32 s20, 0, 0x1c000
	s_add_i32 s21, s73, s23
	v_add_u32_e32 v232, s20, v141
	v_lshl_add_u64 v[138:139], v[138:139], 0, s[28:29]
	s_mov_b32 m0, s21
	ds_read_b128 v[220:223], v232
	ds_read_b128 v[224:227], v232 offset:1024
	ds_read_b128 v[228:231], v232 offset:2048
	ds_read_b128 v[232:235], v232 offset:3072
	global_load_lds_dwordx4 v[138:139], off
	v_lshl_add_u64 v[138:139], v[174:175], 0, s[28:29]
	s_add_i32 m0, s21, 0x2000
	s_nop 0
	global_load_lds_dwordx4 v[138:139], off
	s_barrier
	s_waitcnt lgkmcnt(3)
	v_mfma_f32_16x16x32_bf16 v[116:119], v[220:223], v[188:191], v[116:119]
	s_waitcnt lgkmcnt(1)
	v_mfma_f32_16x16x32_bf16 v[112:115], v[228:231], v[188:191], v[112:115]
	v_mfma_f32_16x16x32_bf16 v[100:103], v[220:223], v[196:199], v[100:103]
	v_mfma_f32_16x16x32_bf16 v[96:99], v[228:231], v[196:199], v[96:99]
	v_mfma_f32_16x16x32_bf16 v[84:87], v[220:223], v[204:207], v[84:87]
	v_mfma_f32_16x16x32_bf16 v[80:83], v[228:231], v[204:207], v[80:83]
	v_mfma_f32_16x16x32_bf16 v[68:71], v[220:223], v[212:215], v[68:71]
	v_mfma_f32_16x16x32_bf16 v[64:67], v[228:231], v[212:215], v[64:67]
	v_mfma_f32_16x16x32_bf16 v[116:119], v[224:227], v[192:195], v[116:119]
	s_waitcnt lgkmcnt(0)
	v_mfma_f32_16x16x32_bf16 v[112:115], v[232:235], v[192:195], v[112:115]
	v_mfma_f32_16x16x32_bf16 v[100:103], v[224:227], v[200:203], v[100:103]
	v_mfma_f32_16x16x32_bf16 v[96:99], v[232:235], v[200:203], v[96:99]
	s_mov_b32 m0, s38
	v_lshl_add_u64 v[138:139], v[236:237], 0, s[28:29]
	v_mfma_f32_16x16x32_bf16 v[84:87], v[224:227], v[208:211], v[84:87]
	v_mfma_f32_16x16x32_bf16 v[80:83], v[232:235], v[208:211], v[80:83]
	v_mfma_f32_16x16x32_bf16 v[68:71], v[224:227], v[216:219], v[68:71]
	v_mfma_f32_16x16x32_bf16 v[64:67], v[232:235], v[216:219], v[64:67]
	s_barrier
	ds_read_b128 v[188:191], v143 offset:49152
	ds_read_b128 v[196:199], v143 offset:51200
	ds_read_b128 v[204:207], v143 offset:53248
	ds_read_b128 v[212:215], v143 offset:55296
	ds_read_b128 v[192:195], v143 offset:50176
	ds_read_b128 v[200:203], v143 offset:52224
	ds_read_b128 v[208:211], v143 offset:54272
	ds_read_b128 v[216:219], v143 offset:56320
	global_load_lds_dwordx4 v[138:139], off
	v_lshl_add_u64 v[138:139], v[238:239], 0, s[28:29]
	s_mov_b32 m0, s39
	s_nop 0
	global_load_lds_dwordx4 v[138:139], off
	s_barrier
	s_waitcnt lgkmcnt(7)
	v_mfma_f32_16x16x32_bf16 v[60:63], v[158:161], v[188:191], v[60:63]
	v_mfma_f32_16x16x32_bf16 v[56:59], v[166:169], v[188:191], v[56:59]
	s_waitcnt lgkmcnt(6)
	v_mfma_f32_16x16x32_bf16 v[44:47], v[158:161], v[196:199], v[44:47]
	v_mfma_f32_16x16x32_bf16 v[40:43], v[166:169], v[196:199], v[40:43]
	s_waitcnt lgkmcnt(5)
	v_mfma_f32_16x16x32_bf16 v[28:31], v[158:161], v[204:207], v[28:31]
	v_mfma_f32_16x16x32_bf16 v[24:27], v[166:169], v[204:207], v[24:27]
	s_waitcnt lgkmcnt(4)
	v_mfma_f32_16x16x32_bf16 v[12:15], v[158:161], v[212:215], v[12:15]
	v_mfma_f32_16x16x32_bf16 v[8:11], v[166:169], v[212:215], v[8:11]
	s_waitcnt lgkmcnt(3)
	v_mfma_f32_16x16x32_bf16 v[60:63], v[162:165], v[192:195], v[60:63]
	v_mfma_f32_16x16x32_bf16 v[56:59], v[170:173], v[192:195], v[56:59]
	s_waitcnt lgkmcnt(2)
	v_mfma_f32_16x16x32_bf16 v[44:47], v[162:165], v[200:203], v[44:47]
	v_mfma_f32_16x16x32_bf16 v[40:43], v[170:173], v[200:203], v[40:43]
	s_waitcnt lgkmcnt(1)
	v_mfma_f32_16x16x32_bf16 v[28:31], v[162:165], v[208:211], v[28:31]
	v_mfma_f32_16x16x32_bf16 v[24:27], v[170:173], v[208:211], v[24:27]
	s_waitcnt lgkmcnt(0)
	v_mfma_f32_16x16x32_bf16 v[12:15], v[162:165], v[216:219], v[12:15]
	v_mfma_f32_16x16x32_bf16 v[8:11], v[170:173], v[216:219], v[8:11]
	s_barrier
	s_add_u32 s14, s14, 0x40080
	s_addc_u32 s15, s15, 0
	s_add_i32 s20, s20, s23
	v_lshl_add_u64 v[138:139], s[14:15], 0, v[148:149]
	s_mov_b32 m0, s20
	s_nop 0
	global_load_lds_dwordx4 v[138:139], off
	v_lshl_add_u64 v[138:139], s[14:15], 0, v[128:129]
	s_add_i32 m0, s20, 0x2000
	s_nop 0
	global_load_lds_dwordx4 v[138:139], off
	s_waitcnt vmcnt(6)
	s_barrier
	v_mfma_f32_16x16x32_bf16 v[52:55], v[220:223], v[188:191], v[52:55]
	v_mfma_f32_16x16x32_bf16 v[48:51], v[228:231], v[188:191], v[48:51]
	v_mfma_f32_16x16x32_bf16 v[36:39], v[220:223], v[196:199], v[36:39]
	v_mfma_f32_16x16x32_bf16 v[32:35], v[228:231], v[196:199], v[32:35]
	v_mfma_f32_16x16x32_bf16 v[20:23], v[220:223], v[204:207], v[20:23]
	v_mfma_f32_16x16x32_bf16 v[16:19], v[228:231], v[204:207], v[16:19]
	v_mfma_f32_16x16x32_bf16 v[4:7], v[220:223], v[212:215], v[4:7]
	v_mfma_f32_16x16x32_bf16 v[0:3], v[228:231], v[212:215], v[0:3]
	v_mfma_f32_16x16x32_bf16 v[52:55], v[224:227], v[192:195], v[52:55]
	v_mfma_f32_16x16x32_bf16 v[48:51], v[232:235], v[192:195], v[48:51]
	v_mfma_f32_16x16x32_bf16 v[36:39], v[224:227], v[200:203], v[36:39]
	v_mfma_f32_16x16x32_bf16 v[32:35], v[232:235], v[200:203], v[32:35]
	s_add_i32 s51, s51, 2
	s_add_u32 s10, s10, 0x100
	s_addc_u32 s11, s11, 0
	s_add_u32 s47, s47, 0x100
	s_addc_u32 s50, s50, 0
	s_cmp_gt_u32 s51, 13
	v_mfma_f32_16x16x32_bf16 v[20:23], v[224:227], v[208:211], v[20:23]
	v_mfma_f32_16x16x32_bf16 v[16:19], v[232:235], v[208:211], v[16:19]
	v_mfma_f32_16x16x32_bf16 v[4:7], v[224:227], v[216:219], v[4:7]
	v_mfma_f32_16x16x32_bf16 v[0:3], v[232:235], v[216:219], v[0:3]
	s_barrier
	s_cbranch_scc1 .Lpeel_after_g1
	.p2align	8
.LBB0_705:
	s_add_u32 s14, s10, 0xfffc0080
	s_addc_u32 s15, s11, -1
	s_add_i32 s73, 0, 0x10000
	v_add_u32_e32 v138, s73, v141
	ds_read_b128 v[158:161], v138
	ds_read_b128 v[162:165], v138 offset:1024
	ds_read_b128 v[166:169], v138 offset:2048
	ds_read_b128 v[170:173], v138 offset:3072
	s_cmp_eq_u32 s51, 12
	s_cselect_b32 s21, s3, s15
	s_cselect_b32 s20, s45, s14
	s_cselect_b32 s15, s1, s50
	s_cselect_b32 s14, s46, s47
	v_lshl_add_u64 v[138:139], s[10:11], 0, v[134:135]
	s_add_i32 m0, s24, 0xc000
	ds_read_b128 v[188:191], v143
	ds_read_b128 v[196:199], v143 offset:2048
	ds_read_b128 v[204:207], v143 offset:4096
	ds_read_b128 v[212:215], v143 offset:6144
	ds_read_b128 v[192:195], v143 offset:1024
	ds_read_b128 v[200:203], v143 offset:3072
	ds_read_b128 v[208:211], v143 offset:5120
	ds_read_b128 v[216:219], v143 offset:7168
	global_load_lds_dwordx4 v[138:139], off
	v_lshl_add_u64 v[138:139], s[10:11], 0, v[136:137]
	s_add_i32 m0, s24, 0xe000
	s_nop 0
	global_load_lds_dwordx4 v[138:139], off
	s_waitcnt lgkmcnt(8)
	s_barrier
	s_waitcnt lgkmcnt(7)
	v_mfma_f32_16x16x32_bf16 v[124:127], v[158:161], v[188:191], v[124:127]
	v_mfma_f32_16x16x32_bf16 v[120:123], v[166:169], v[188:191], v[120:123]
	s_waitcnt lgkmcnt(6)
	v_mfma_f32_16x16x32_bf16 v[108:111], v[158:161], v[196:199], v[108:111]
	v_mfma_f32_16x16x32_bf16 v[104:107], v[166:169], v[196:199], v[104:107]
	s_waitcnt lgkmcnt(5)
	v_mfma_f32_16x16x32_bf16 v[92:95], v[158:161], v[204:207], v[92:95]
	v_mfma_f32_16x16x32_bf16 v[88:91], v[166:169], v[204:207], v[88:91]
	s_waitcnt lgkmcnt(4)
	v_mfma_f32_16x16x32_bf16 v[76:79], v[158:161], v[212:215], v[76:79]
	v_mfma_f32_16x16x32_bf16 v[72:75], v[166:169], v[212:215], v[72:75]
	s_waitcnt lgkmcnt(3)
	v_mfma_f32_16x16x32_bf16 v[124:127], v[162:165], v[192:195], v[124:127]
	v_mfma_f32_16x16x32_bf16 v[120:123], v[170:173], v[192:195], v[120:123]
	s_waitcnt lgkmcnt(2)
	v_mfma_f32_16x16x32_bf16 v[108:111], v[162:165], v[200:203], v[108:111]
	v_mfma_f32_16x16x32_bf16 v[104:107], v[170:173], v[200:203], v[104:107]
	s_waitcnt lgkmcnt(1)
	v_mfma_f32_16x16x32_bf16 v[92:95], v[162:165], v[208:211], v[92:95]
	v_mfma_f32_16x16x32_bf16 v[88:91], v[170:173], v[208:211], v[88:91]
	s_waitcnt lgkmcnt(0)
	v_mfma_f32_16x16x32_bf16 v[76:79], v[162:165], v[216:219], v[76:79]
	v_mfma_f32_16x16x32_bf16 v[72:75], v[170:173], v[216:219], v[72:75]
	s_barrier
	s_add_i32 s78, 0, 0x14000
	v_add_u32_e32 v138, s78, v141
	s_add_i32 s73, s73, s23
	ds_read_b128 v[220:223], v138
	ds_read_b128 v[224:227], v138 offset:1024
	ds_read_b128 v[228:231], v138 offset:2048
	ds_read_b128 v[232:235], v138 offset:3072
	v_lshl_add_u64 v[138:139], s[14:15], 0, v[148:149]
	s_mov_b32 m0, s73
	v_lshl_add_u64 v[174:175], s[14:15], 0, v[128:129]
	global_load_lds_dwordx4 v[138:139], off
	s_add_i32 m0, s73, 0x2000
	s_nop 0
	global_load_lds_dwordx4 v[174:175], off
	s_barrier
	s_waitcnt lgkmcnt(3)
	v_mfma_f32_16x16x32_bf16 v[116:119], v[220:223], v[188:191], v[116:119]
	s_waitcnt lgkmcnt(1)
	v_mfma_f32_16x16x32_bf16 v[112:115], v[228:231], v[188:191], v[112:115]
	v_mfma_f32_16x16x32_bf16 v[100:103], v[220:223], v[196:199], v[100:103]
	v_mfma_f32_16x16x32_bf16 v[96:99], v[228:231], v[196:199], v[96:99]
	v_mfma_f32_16x16x32_bf16 v[84:87], v[220:223], v[204:207], v[84:87]
	v_mfma_f32_16x16x32_bf16 v[80:83], v[228:231], v[204:207], v[80:83]
	v_mfma_f32_16x16x32_bf16 v[68:71], v[220:223], v[212:215], v[68:71]
	v_mfma_f32_16x16x32_bf16 v[64:67], v[228:231], v[212:215], v[64:67]
	v_mfma_f32_16x16x32_bf16 v[116:119], v[224:227], v[192:195], v[116:119]
	s_waitcnt lgkmcnt(0)
	v_mfma_f32_16x16x32_bf16 v[112:115], v[232:235], v[192:195], v[112:115]
	v_mfma_f32_16x16x32_bf16 v[100:103], v[224:227], v[200:203], v[100:103]
	v_mfma_f32_16x16x32_bf16 v[96:99], v[232:235], v[200:203], v[96:99]
	s_mov_b32 m0, s24
	v_lshl_add_u64 v[236:237], s[20:21], 0, v[132:133]
	v_mfma_f32_16x16x32_bf16 v[84:87], v[224:227], v[208:211], v[84:87]
	v_mfma_f32_16x16x32_bf16 v[80:83], v[232:235], v[208:211], v[80:83]
	v_mfma_f32_16x16x32_bf16 v[68:71], v[224:227], v[216:219], v[68:71]
	v_mfma_f32_16x16x32_bf16 v[64:67], v[232:235], v[216:219], v[64:67]
	s_barrier
	ds_read_b128 v[188:191], v143 offset:16384
	ds_read_b128 v[196:199], v143 offset:18432
	ds_read_b128 v[204:207], v143 offset:20480
	ds_read_b128 v[212:215], v143 offset:22528
	ds_read_b128 v[192:195], v143 offset:17408
	ds_read_b128 v[200:203], v143 offset:19456
	ds_read_b128 v[208:211], v143 offset:21504
	ds_read_b128 v[216:219], v143 offset:23552
	global_load_lds_dwordx4 v[236:237], off
	v_lshl_add_u64 v[238:239], s[20:21], 0, v[130:131]
	s_mov_b32 m0, s25
	s_nop 0
	global_load_lds_dwordx4 v[238:239], off
	s_barrier
	s_waitcnt lgkmcnt(7)
	v_mfma_f32_16x16x32_bf16 v[60:63], v[158:161], v[188:191], v[60:63]
	v_mfma_f32_16x16x32_bf16 v[56:59], v[166:169], v[188:191], v[56:59]
	s_waitcnt lgkmcnt(6)
	v_mfma_f32_16x16x32_bf16 v[44:47], v[158:161], v[196:199], v[44:47]
	v_mfma_f32_16x16x32_bf16 v[40:43], v[166:169], v[196:199], v[40:43]
	s_waitcnt lgkmcnt(5)
	v_mfma_f32_16x16x32_bf16 v[28:31], v[158:161], v[204:207], v[28:31]
	v_mfma_f32_16x16x32_bf16 v[24:27], v[166:169], v[204:207], v[24:27]
	s_waitcnt lgkmcnt(4)
	v_mfma_f32_16x16x32_bf16 v[12:15], v[158:161], v[212:215], v[12:15]
	v_mfma_f32_16x16x32_bf16 v[8:11], v[166:169], v[212:215], v[8:11]
	s_waitcnt lgkmcnt(3)
	v_mfma_f32_16x16x32_bf16 v[60:63], v[162:165], v[192:195], v[60:63]
	v_mfma_f32_16x16x32_bf16 v[56:59], v[170:173], v[192:195], v[56:59]
	s_waitcnt lgkmcnt(2)
	v_mfma_f32_16x16x32_bf16 v[44:47], v[162:165], v[200:203], v[44:47]
	v_mfma_f32_16x16x32_bf16 v[40:43], v[170:173], v[200:203], v[40:43]
	s_waitcnt lgkmcnt(1)
	v_mfma_f32_16x16x32_bf16 v[28:31], v[162:165], v[208:211], v[28:31]
	v_mfma_f32_16x16x32_bf16 v[24:27], v[170:173], v[208:211], v[24:27]
	s_waitcnt lgkmcnt(0)
	v_mfma_f32_16x16x32_bf16 v[12:15], v[162:165], v[216:219], v[12:15]
	v_mfma_f32_16x16x32_bf16 v[8:11], v[170:173], v[216:219], v[8:11]
	s_barrier
	s_add_u32 s74, s14, 0x40000
	s_addc_u32 s75, s15, 0
	s_add_i32 s73, s78, s23
	v_lshl_add_u64 v[158:159], s[74:75], 0, v[148:149]
	s_mov_b32 m0, s73
	s_nop 0
	global_load_lds_dwordx4 v[158:159], off
	v_lshl_add_u64 v[158:159], s[74:75], 0, v[128:129]
	s_add_i32 m0, s73, 0x2000
	s_nop 0
	global_load_lds_dwordx4 v[158:159], off
	s_waitcnt vmcnt(6)
	s_barrier
	v_mfma_f32_16x16x32_bf16 v[52:55], v[220:223], v[188:191], v[52:55]
	v_mfma_f32_16x16x32_bf16 v[48:51], v[228:231], v[188:191], v[48:51]
	v_mfma_f32_16x16x32_bf16 v[36:39], v[220:223], v[196:199], v[36:39]
	v_mfma_f32_16x16x32_bf16 v[32:35], v[228:231], v[196:199], v[32:35]
	v_mfma_f32_16x16x32_bf16 v[20:23], v[220:223], v[204:207], v[20:23]
	v_mfma_f32_16x16x32_bf16 v[16:19], v[228:231], v[204:207], v[16:19]
	v_mfma_f32_16x16x32_bf16 v[4:7], v[220:223], v[212:215], v[4:7]
	v_mfma_f32_16x16x32_bf16 v[0:3], v[228:231], v[212:215], v[0:3]
	v_mfma_f32_16x16x32_bf16 v[52:55], v[224:227], v[192:195], v[52:55]
	v_mfma_f32_16x16x32_bf16 v[48:51], v[232:235], v[192:195], v[48:51]
	v_mfma_f32_16x16x32_bf16 v[36:39], v[224:227], v[200:203], v[36:39]
	v_mfma_f32_16x16x32_bf16 v[32:35], v[232:235], v[200:203], v[32:35]
	s_add_i32 s73, 0, 0x18000
	v_add_u32_e32 v170, s73, v141
	v_mfma_f32_16x16x32_bf16 v[20:23], v[224:227], v[208:211], v[20:23]
	v_mfma_f32_16x16x32_bf16 v[16:19], v[232:235], v[208:211], v[16:19]
	v_mfma_f32_16x16x32_bf16 v[4:7], v[224:227], v[216:219], v[4:7]
	v_mfma_f32_16x16x32_bf16 v[0:3], v[232:235], v[216:219], v[0:3]
	s_barrier
	ds_read_b128 v[158:161], v170
	ds_read_b128 v[162:165], v170 offset:1024
	ds_read_b128 v[166:169], v170 offset:2048
	ds_read_b128 v[170:173], v170 offset:3072
	s_add_u32 s20, s20, 0x40000
	s_addc_u32 s21, s21, 0
	s_mov_b32 m0, s36
	v_lshl_add_u64 v[220:221], s[20:21], 0, v[132:133]
	ds_read_b128 v[188:191], v143 offset:32768
	ds_read_b128 v[196:199], v143 offset:34816
	ds_read_b128 v[204:207], v143 offset:36864
	ds_read_b128 v[212:215], v143 offset:38912
	ds_read_b128 v[192:195], v143 offset:33792
	ds_read_b128 v[200:203], v143 offset:35840
	ds_read_b128 v[208:211], v143 offset:37888
	ds_read_b128 v[216:219], v143 offset:39936
	global_load_lds_dwordx4 v[220:221], off
	v_lshl_add_u64 v[220:221], s[20:21], 0, v[130:131]
	s_mov_b32 m0, s37
	s_nop 0
	global_load_lds_dwordx4 v[220:221], off
	s_waitcnt lgkmcnt(8)
	s_barrier
	s_waitcnt lgkmcnt(7)
	v_mfma_f32_16x16x32_bf16 v[124:127], v[158:161], v[188:191], v[124:127]
	v_mfma_f32_16x16x32_bf16 v[120:123], v[166:169], v[188:191], v[120:123]
	s_waitcnt lgkmcnt(6)
	v_mfma_f32_16x16x32_bf16 v[108:111], v[158:161], v[196:199], v[108:111]
	v_mfma_f32_16x16x32_bf16 v[104:107], v[166:169], v[196:199], v[104:107]
	s_waitcnt lgkmcnt(5)
	v_mfma_f32_16x16x32_bf16 v[92:95], v[158:161], v[204:207], v[92:95]
	v_mfma_f32_16x16x32_bf16 v[88:91], v[166:169], v[204:207], v[88:91]
	s_waitcnt lgkmcnt(4)
	v_mfma_f32_16x16x32_bf16 v[76:79], v[158:161], v[212:215], v[76:79]
	v_mfma_f32_16x16x32_bf16 v[72:75], v[166:169], v[212:215], v[72:75]
	s_waitcnt lgkmcnt(3)
	v_mfma_f32_16x16x32_bf16 v[124:127], v[162:165], v[192:195], v[124:127]
	v_mfma_f32_16x16x32_bf16 v[120:123], v[170:173], v[192:195], v[120:123]
	s_waitcnt lgkmcnt(2)
	v_mfma_f32_16x16x32_bf16 v[108:111], v[162:165], v[200:203], v[108:111]
	v_mfma_f32_16x16x32_bf16 v[104:107], v[170:173], v[200:203], v[104:107]
	s_waitcnt lgkmcnt(1)
	v_mfma_f32_16x16x32_bf16 v[92:95], v[162:165], v[208:211], v[92:95]
	v_mfma_f32_16x16x32_bf16 v[88:91], v[170:173], v[208:211], v[88:91]
	s_waitcnt lgkmcnt(0)
	v_mfma_f32_16x16x32_bf16 v[76:79], v[162:165], v[216:219], v[76:79]
	v_mfma_f32_16x16x32_bf16 v[72:75], v[170:173], v[216:219], v[72:75]
	s_barrier
	s_add_i32 s20, 0, 0x1c000
	s_add_i32 s21, s73, s23
	v_add_u32_e32 v232, s20, v141
	v_lshl_add_u64 v[138:139], v[138:139], 0, s[28:29]
	s_mov_b32 m0, s21
	ds_read_b128 v[220:223], v232
	ds_read_b128 v[224:227], v232 offset:1024
	ds_read_b128 v[228:231], v232 offset:2048
	ds_read_b128 v[232:235], v232 offset:3072
	global_load_lds_dwordx4 v[138:139], off
	v_lshl_add_u64 v[138:139], v[174:175], 0, s[28:29]
	s_add_i32 m0, s21, 0x2000
	s_nop 0
	global_load_lds_dwordx4 v[138:139], off
	s_barrier
	s_waitcnt lgkmcnt(3)
	v_mfma_f32_16x16x32_bf16 v[116:119], v[220:223], v[188:191], v[116:119]
	s_waitcnt lgkmcnt(1)
	v_mfma_f32_16x16x32_bf16 v[112:115], v[228:231], v[188:191], v[112:115]
	v_mfma_f32_16x16x32_bf16 v[100:103], v[220:223], v[196:199], v[100:103]
	v_mfma_f32_16x16x32_bf16 v[96:99], v[228:231], v[196:199], v[96:99]
	v_mfma_f32_16x16x32_bf16 v[84:87], v[220:223], v[204:207], v[84:87]
	v_mfma_f32_16x16x32_bf16 v[80:83], v[228:231], v[204:207], v[80:83]
	v_mfma_f32_16x16x32_bf16 v[68:71], v[220:223], v[212:215], v[68:71]
	v_mfma_f32_16x16x32_bf16 v[64:67], v[228:231], v[212:215], v[64:67]
	v_mfma_f32_16x16x32_bf16 v[116:119], v[224:227], v[192:195], v[116:119]
	s_waitcnt lgkmcnt(0)
	v_mfma_f32_16x16x32_bf16 v[112:115], v[232:235], v[192:195], v[112:115]
	v_mfma_f32_16x16x32_bf16 v[100:103], v[224:227], v[200:203], v[100:103]
	v_mfma_f32_16x16x32_bf16 v[96:99], v[232:235], v[200:203], v[96:99]
	s_mov_b32 m0, s38
	v_lshl_add_u64 v[138:139], v[236:237], 0, s[28:29]
	v_mfma_f32_16x16x32_bf16 v[84:87], v[224:227], v[208:211], v[84:87]
	v_mfma_f32_16x16x32_bf16 v[80:83], v[232:235], v[208:211], v[80:83]
	v_mfma_f32_16x16x32_bf16 v[68:71], v[224:227], v[216:219], v[68:71]
	v_mfma_f32_16x16x32_bf16 v[64:67], v[232:235], v[216:219], v[64:67]
	s_barrier
	ds_read_b128 v[188:191], v143 offset:49152
	ds_read_b128 v[196:199], v143 offset:51200
	ds_read_b128 v[204:207], v143 offset:53248
	ds_read_b128 v[212:215], v143 offset:55296
	ds_read_b128 v[192:195], v143 offset:50176
	ds_read_b128 v[200:203], v143 offset:52224
	ds_read_b128 v[208:211], v143 offset:54272
	ds_read_b128 v[216:219], v143 offset:56320
	global_load_lds_dwordx4 v[138:139], off
	v_lshl_add_u64 v[138:139], v[238:239], 0, s[28:29]
	s_mov_b32 m0, s39
	s_nop 0
	global_load_lds_dwordx4 v[138:139], off
	s_barrier
	s_waitcnt lgkmcnt(7)
	v_mfma_f32_16x16x32_bf16 v[60:63], v[158:161], v[188:191], v[60:63]
	v_mfma_f32_16x16x32_bf16 v[56:59], v[166:169], v[188:191], v[56:59]
	s_waitcnt lgkmcnt(6)
	v_mfma_f32_16x16x32_bf16 v[44:47], v[158:161], v[196:199], v[44:47]
	v_mfma_f32_16x16x32_bf16 v[40:43], v[166:169], v[196:199], v[40:43]
	s_waitcnt lgkmcnt(5)
	v_mfma_f32_16x16x32_bf16 v[28:31], v[158:161], v[204:207], v[28:31]
	v_mfma_f32_16x16x32_bf16 v[24:27], v[166:169], v[204:207], v[24:27]
	s_waitcnt lgkmcnt(4)
	v_mfma_f32_16x16x32_bf16 v[12:15], v[158:161], v[212:215], v[12:15]
	v_mfma_f32_16x16x32_bf16 v[8:11], v[166:169], v[212:215], v[8:11]
	s_waitcnt lgkmcnt(3)
	v_mfma_f32_16x16x32_bf16 v[60:63], v[162:165], v[192:195], v[60:63]
	v_mfma_f32_16x16x32_bf16 v[56:59], v[170:173], v[192:195], v[56:59]
	s_waitcnt lgkmcnt(2)
	v_mfma_f32_16x16x32_bf16 v[44:47], v[162:165], v[200:203], v[44:47]
	v_mfma_f32_16x16x32_bf16 v[40:43], v[170:173], v[200:203], v[40:43]
	s_waitcnt lgkmcnt(1)
	v_mfma_f32_16x16x32_bf16 v[28:31], v[162:165], v[208:211], v[28:31]
	v_mfma_f32_16x16x32_bf16 v[24:27], v[170:173], v[208:211], v[24:27]
	s_waitcnt lgkmcnt(0)
	v_mfma_f32_16x16x32_bf16 v[12:15], v[162:165], v[216:219], v[12:15]
	v_mfma_f32_16x16x32_bf16 v[8:11], v[170:173], v[216:219], v[8:11]
	s_barrier
	s_add_u32 s14, s14, 0x40080
	s_addc_u32 s15, s15, 0
	s_add_i32 s20, s20, s23
	v_lshl_add_u64 v[138:139], s[14:15], 0, v[148:149]
	s_mov_b32 m0, s20
	s_nop 0
	global_load_lds_dwordx4 v[138:139], off
	v_lshl_add_u64 v[138:139], s[14:15], 0, v[128:129]
	s_add_i32 m0, s20, 0x2000
	s_nop 0
	global_load_lds_dwordx4 v[138:139], off
	s_waitcnt vmcnt(6)
	s_barrier
	v_mfma_f32_16x16x32_bf16 v[52:55], v[220:223], v[188:191], v[52:55]
	v_mfma_f32_16x16x32_bf16 v[48:51], v[228:231], v[188:191], v[48:51]
	v_mfma_f32_16x16x32_bf16 v[36:39], v[220:223], v[196:199], v[36:39]
	v_mfma_f32_16x16x32_bf16 v[32:35], v[228:231], v[196:199], v[32:35]
	v_mfma_f32_16x16x32_bf16 v[20:23], v[220:223], v[204:207], v[20:23]
	v_mfma_f32_16x16x32_bf16 v[16:19], v[228:231], v[204:207], v[16:19]
	v_mfma_f32_16x16x32_bf16 v[4:7], v[220:223], v[212:215], v[4:7]
	v_mfma_f32_16x16x32_bf16 v[0:3], v[228:231], v[212:215], v[0:3]
	v_mfma_f32_16x16x32_bf16 v[52:55], v[224:227], v[192:195], v[52:55]
	v_mfma_f32_16x16x32_bf16 v[48:51], v[232:235], v[192:195], v[48:51]
	v_mfma_f32_16x16x32_bf16 v[36:39], v[224:227], v[200:203], v[36:39]
	v_mfma_f32_16x16x32_bf16 v[32:35], v[232:235], v[200:203], v[32:35]
	s_add_i32 s51, s51, 2
	s_add_u32 s10, s10, 0x100
	s_addc_u32 s11, s11, 0
	s_add_u32 s47, s47, 0x100
	s_addc_u32 s50, s50, 0
	s_cmp_gt_u32 s51, 13
	v_mfma_f32_16x16x32_bf16 v[20:23], v[224:227], v[208:211], v[20:23]
	v_mfma_f32_16x16x32_bf16 v[16:19], v[232:235], v[208:211], v[16:19]
	v_mfma_f32_16x16x32_bf16 v[4:7], v[224:227], v[216:219], v[4:7]
	v_mfma_f32_16x16x32_bf16 v[0:3], v[232:235], v[216:219], v[0:3]
	s_barrier
	s_cbranch_scc0 .LBB0_705
